# mLSTM: next-chunk register prefetch issued behind the q-fragment vmcnt waits instead of in front of them (those waits drained the fresh prefetch on every chunk)
# baseline (speedup 1.0000x reference)
.LBB0_663:
	ds_read_b32 v182, v140
	s_waitcnt vmcnt(3)
	v_and_b32_e32 v199, 0xffff0000, v78
	v_lshlrev_b32_e32 v198, 16, v78
	s_waitcnt vmcnt(2)
	v_and_b32_e32 v231, 0xffff0000, v74
	v_and_b32_e32 v230, 0xffff0000, v80
	s_waitcnt lgkmcnt(0)
	v_sub_f32_e32 v82, v181, v182
	v_mul_f32_e32 v183, 0x3fb8aa3b, v82
	ds_read_b128 v[82:85], v152
	ds_read_b128 v[86:89], v152 offset:1088
	ds_read_b128 v[90:93], v152 offset:64
	ds_read_b128 v[94:97], v152 offset:1152
	v_readlane_b32 s16, v254, 25
	s_waitcnt lgkmcnt(3)
	v_mfma_f32_16x16x32_bf16 v[82:85], v[82:85], v[78:81], 0
	v_readlane_b32 s17, v254, 26
	v_lshlrev_b64 v[132:133], 10, v[132:133]
	s_mov_b32 s0, 0
	s_waitcnt lgkmcnt(2)
	v_mfma_f32_16x16x32_bf16 v[86:89], v[86:89], v[78:81], 0
	s_waitcnt lgkmcnt(1)
	v_mfma_f32_16x16x32_bf16 v[82:85], v[90:93], v[74:77], v[82:85]
	s_waitcnt lgkmcnt(0)
	v_mfma_f32_16x16x32_bf16 v[86:89], v[94:97], v[74:77], v[86:89]
	ds_read_b128 v[90:93], v152 offset:128
	ds_read_b128 v[94:97], v152 offset:1216
	s_waitcnt vmcnt(1) lgkmcnt(1)
	v_mfma_f32_16x16x32_bf16 v[82:85], v[90:93], v[70:73], v[82:85]
	s_waitcnt lgkmcnt(0)
	v_mfma_f32_16x16x32_bf16 v[86:89], v[94:97], v[70:73], v[86:89]
	ds_read_b128 v[90:93], v152 offset:192
	ds_read_b128 v[94:97], v152 offset:1280
	s_waitcnt vmcnt(0) lgkmcnt(1)
	v_mfma_f32_16x16x32_bf16 v[82:85], v[90:93], v[66:69], v[82:85]
	s_andn2_b64 vcc, exec, s[96:97]
	s_cbranch_vccnz .Lml_pf_skip0
	global_load_dwordx4 v[2:5], v[112:113], off offset:1024
	global_load_dwordx4 v[6:9], v[114:115], off offset:1024
	global_load_dwordx4 v[10:13], v[116:117], off offset:1024
	global_load_dwordx4 v[14:17], v[118:119], off offset:1024
	s_and_saveexec_b64 s[90:91], s[8:9]
	s_cbranch_execz .LBB0_660
	global_load_dwordx4 v[18:21], v[120:121], off
	global_load_dwordx4 v[22:25], v[122:123], off
	global_load_dwordx4 v[26:29], v[124:125], off
	global_load_dwordx4 v[30:33], v[126:127], off

.Lml_pf_skip0:
	s_waitcnt lgkmcnt(0)
	v_mfma_f32_16x16x32_bf16 v[86:89], v[94:97], v[66:69], v[86:89]
	ds_read_b128 v[90:93], v142
	ds_read_b128 v[94:97], v142 offset:16
	s_waitcnt lgkmcnt(1)
	v_sub_f32_e32 v90, v90, v182
	v_sub_f32_e32 v91, v91, v182
	v_mul_f32_e32 v90, 0x3fb8aa3b, v90
	v_mul_f32_e32 v91, 0x3fb8aa3b, v91
	v_exp_f32_e32 v90, v90
	v_exp_f32_e32 v91, v91
	v_mul_f32_e32 v82, v82, v90
	v_mul_f32_e32 v83, v83, v91
	v_cndmask_b32_e64 v90, v82, 0, s[24:25]
	s_waitcnt lgkmcnt(0)
	v_sub_f32_e32 v82, v94, v182
	v_cndmask_b32_e64 v91, 0, v83, s[26:27]
	v_sub_f32_e32 v83, v95, v182
	v_mul_f32_e32 v82, 0x3fb8aa3b, v82
	v_mul_f32_e32 v83, 0x3fb8aa3b, v83
	v_exp_f32_e32 v82, v82
	v_exp_f32_e32 v83, v83
	s_nop 0
	v_pk_mul_f32 v[82:83], v[86:87], v[82:83]
	s_nop 0
	v_cndmask_b32_e64 v95, v83, 0, s[28:29]
	v_sub_f32_e32 v83, v96, v182
	v_mul_f32_e32 v83, 0x3fb8aa3b, v83
	v_cndmask_b32_e64 v98, v82, 0, s[30:31]
	v_sub_f32_e32 v82, v92, v182
	v_exp_f32_e32 v86, v83
	v_sub_f32_e32 v83, v93, v182
	v_mul_f32_e32 v82, 0x3fb8aa3b, v82
	v_mul_f32_e32 v83, 0x3fb8aa3b, v83
	v_exp_f32_e32 v82, v82
	v_exp_f32_e32 v83, v83
	s_nop 0
	v_pk_mul_f32 v[82:83], v[84:85], v[82:83]
	s_nop 0
	v_cndmask_b32_e64 v85, v82, 0, s[36:37]
	v_sub_f32_e32 v82, v97, v182
	v_mul_f32_e32 v82, 0x3fb8aa3b, v82
	v_exp_f32_e32 v87, v82
	v_cndmask_b32_e64 v84, v83, 0, s[34:35]
	v_pk_mul_f32 v[82:83], v[88:89], v[86:87]
	s_nop 0
	v_cndmask_b32_e64 v87, v82, 0, s[40:41]
	v_add_f32_e32 v82, 0, v90
	v_add_f32_e32 v82, v91, v82
	v_add_f32_e32 v82, v85, v82
	v_add_f32_e32 v82, v84, v82
	v_add_f32_e32 v82, v98, v82
	v_add_f32_e32 v82, v95, v82
	v_cndmask_b32_e64 v86, v83, 0, s[38:39]
	v_add_f32_e32 v82, v87, v82
	v_add_f32_e32 v94, v86, v82
	v_cvt_pk_bf16_f32 v82, v90, v91
	v_cvt_pk_bf16_f32 v83, v85, v84
	v_cvt_pk_bf16_f32 v85, v87, v86
	ds_read_b128 v[86:89], v152 offset:8704
	ds_read_b128 v[90:93], v152 offset:9792
	v_cvt_pk_bf16_f32 v84, v98, v95
	ds_read_b128 v[96:99], v152 offset:8768
	ds_read_b128 v[184:187], v152 offset:9856
	s_waitcnt lgkmcnt(3)
	v_mfma_f32_16x16x32_bf16 v[86:89], v[86:89], v[78:81], 0
	s_waitcnt lgkmcnt(2)
	v_mfma_f32_16x16x32_bf16 v[90:93], v[90:93], v[78:81], 0
	s_waitcnt lgkmcnt(1)
	v_mfma_f32_16x16x32_bf16 v[86:89], v[96:99], v[74:77], v[86:89]
	s_waitcnt lgkmcnt(0)
	v_mfma_f32_16x16x32_bf16 v[90:93], v[184:187], v[74:77], v[90:93]
	ds_read_b128 v[96:99], v152 offset:8832
	ds_read_b128 v[184:187], v152 offset:9920
	s_waitcnt lgkmcnt(1)
	v_mfma_f32_16x16x32_bf16 v[86:89], v[96:99], v[70:73], v[86:89]
	s_waitcnt lgkmcnt(0)
	v_mfma_f32_16x16x32_bf16 v[96:99], v[184:187], v[70:73], v[90:93]
	s_nop 2
	ds_read_b128 v[90:93], v152 offset:8896
	ds_read_b128 v[184:187], v152 offset:9984
	s_waitcnt lgkmcnt(1)
	v_mfma_f32_16x16x32_bf16 v[90:93], v[90:93], v[66:69], v[86:89]
	s_waitcnt lgkmcnt(0)
	v_mfma_f32_16x16x32_bf16 v[86:89], v[184:187], v[66:69], v[96:99]
	s_nop 2
	ds_read_b128 v[96:99], v142 offset:128
	ds_read_b128 v[184:187], v142 offset:144
	s_waitcnt lgkmcnt(1)
	v_sub_f32_e32 v95, v96, v182
	v_mul_f32_e32 v95, 0x3fb8aa3b, v95
	v_exp_f32_e32 v96, v95
	s_waitcnt lgkmcnt(0)
	v_sub_f32_e32 v95, v184, v182
	v_mul_f32_e32 v95, 0x3fb8aa3b, v95
	v_exp_f32_e32 v100, v95
	v_sub_f32_e32 v95, v97, v182
	v_mul_f32_e32 v95, 0x3fb8aa3b, v95
	v_exp_f32_e32 v97, v95
	s_nop 0
	v_pk_mul_f32 v[90:91], v[90:91], v[96:97]
	s_nop 0
	v_cndmask_b32_e64 v96, v90, 0, s[44:45]
	v_sub_f32_e32 v90, v185, v182
	v_mul_f32_e32 v90, 0x3fb8aa3b, v90
	v_exp_f32_e32 v101, v90
	v_cndmask_b32_e64 v95, v91, 0, s[42:43]
	v_pk_mul_f32 v[86:87], v[86:87], v[100:101]
	s_nop 0
	v_cndmask_b32_e64 v97, v87, 0, s[46:47]
	v_sub_f32_e32 v87, v186, v182
	v_mul_f32_e32 v87, 0x3fb8aa3b, v87
	v_cndmask_b32_e64 v100, v86, 0, s[48:49]
	v_sub_f32_e32 v86, v98, v182
	v_exp_f32_e32 v90, v87
	v_sub_f32_e32 v87, v99, v182
	v_mul_f32_e32 v86, 0x3fb8aa3b, v86
	v_mul_f32_e32 v87, 0x3fb8aa3b, v87
	v_exp_f32_e32 v86, v86
	v_exp_f32_e32 v87, v87
	s_nop 0
	v_pk_mul_f32 v[86:87], v[92:93], v[86:87]
	s_nop 0
	v_cndmask_b32_e64 v93, v86, 0, s[52:53]
	v_sub_f32_e32 v86, v187, v182
	v_mul_f32_e32 v86, 0x3fb8aa3b, v86
	v_exp_f32_e32 v91, v86
	v_cndmask_b32_e64 v92, v87, 0, s[50:51]
	v_pk_mul_f32 v[86:87], v[88:89], v[90:91]
	s_nop 0
	v_cndmask_b32_e64 v90, v86, 0, s[56:57]
	v_add_f32_e32 v86, v94, v96
	v_add_f32_e32 v86, v95, v86
	v_add_f32_e32 v86, v93, v86
	v_add_f32_e32 v86, v92, v86
	v_add_f32_e32 v86, v100, v86
	v_add_f32_e32 v86, v97, v86
	v_cndmask_b32_e64 v89, v87, 0, s[54:55]
	v_add_f32_e32 v86, v90, v86
	v_add_f32_e32 v98, v89, v86
	v_cvt_pk_bf16_f32 v86, v96, v95
	v_cvt_pk_bf16_f32 v87, v93, v92
	v_cvt_pk_bf16_f32 v88, v100, v97
	v_cvt_pk_bf16_f32 v89, v90, v89
	ds_read_b128 v[90:93], v152 offset:17408
	ds_read_b128 v[94:97], v152 offset:18496
	ds_read_b128 v[184:187], v152 offset:17472
	ds_read_b128 v[188:191], v152 offset:18560
	s_waitcnt lgkmcnt(3)
	v_mfma_f32_16x16x32_bf16 v[90:93], v[90:93], v[78:81], 0
	s_waitcnt lgkmcnt(2)
	v_mfma_f32_16x16x32_bf16 v[94:97], v[94:97], v[78:81], 0
	s_waitcnt lgkmcnt(1)
	v_mfma_f32_16x16x32_bf16 v[90:93], v[184:187], v[74:77], v[90:93]
	s_waitcnt lgkmcnt(0)
	v_mfma_f32_16x16x32_bf16 v[94:97], v[188:191], v[74:77], v[94:97]
	ds_read_b128 v[184:187], v152 offset:17536
	ds_read_b128 v[188:191], v152 offset:18624
	s_waitcnt lgkmcnt(1)
	v_mfma_f32_16x16x32_bf16 v[90:93], v[184:187], v[70:73], v[90:93]
	s_waitcnt lgkmcnt(0)
	v_mfma_f32_16x16x32_bf16 v[184:187], v[188:191], v[70:73], v[94:97]
	s_nop 2
	ds_read_b128 v[94:97], v152 offset:17600
	ds_read_b128 v[188:191], v152 offset:18688
	s_waitcnt lgkmcnt(1)
	v_mfma_f32_16x16x32_bf16 v[94:97], v[94:97], v[66:69], v[90:93]
	s_waitcnt lgkmcnt(0)
	v_mfma_f32_16x16x32_bf16 v[90:93], v[188:191], v[66:69], v[184:187]
	s_nop 2
	ds_read_b128 v[184:187], v142 offset:256
	ds_read_b128 v[188:191], v142 offset:272
	s_waitcnt lgkmcnt(1)
	v_sub_f32_e32 v99, v184, v182
	v_mul_f32_e32 v99, 0x3fb8aa3b, v99
	v_exp_f32_e32 v100, v99
	s_waitcnt lgkmcnt(0)
	v_sub_f32_e32 v99, v188, v182
	v_mul_f32_e32 v99, 0x3fb8aa3b, v99
	v_exp_f32_e32 v184, v99
	v_sub_f32_e32 v99, v185, v182
	v_mul_f32_e32 v99, 0x3fb8aa3b, v99
	v_exp_f32_e32 v101, v99
	s_nop 0
	v_pk_mul_f32 v[94:95], v[94:95], v[100:101]
	s_nop 0
	v_cndmask_b32_e64 v100, v94, 0, s[60:61]
	v_sub_f32_e32 v94, v189, v182
	v_mul_f32_e32 v94, 0x3fb8aa3b, v94
	v_exp_f32_e32 v185, v94
	v_cndmask_b32_e64 v99, v95, 0, s[58:59]
	v_pk_mul_f32 v[90:91], v[90:91], v[184:185]
	s_nop 0
	v_cndmask_b32_e64 v101, v91, 0, s[62:63]
	v_sub_f32_e32 v91, v190, v182
	v_mul_f32_e32 v91, 0x3fb8aa3b, v91
	v_cndmask_b32_e64 v172, v90, 0, s[64:65]
	v_sub_f32_e32 v90, v186, v182
	v_exp_f32_e32 v94, v91
	v_sub_f32_e32 v91, v187, v182
	v_mul_f32_e32 v90, 0x3fb8aa3b, v90
	v_mul_f32_e32 v91, 0x3fb8aa3b, v91
	v_exp_f32_e32 v90, v90
	v_exp_f32_e32 v91, v91
	s_nop 0
	v_pk_mul_f32 v[90:91], v[96:97], v[90:91]
	s_nop 0
	v_cndmask_b32_e64 v97, v90, 0, s[68:69]
	v_sub_f32_e32 v90, v191, v182
	v_mul_f32_e32 v90, 0x3fb8aa3b, v90
	v_exp_f32_e32 v95, v90
	v_cndmask_b32_e64 v96, v91, 0, s[66:67]
	v_pk_mul_f32 v[90:91], v[92:93], v[94:95]
	s_nop 0
	v_cndmask_b32_e64 v94, v90, 0, s[72:73]
	v_add_f32_e32 v90, v98, v100
	v_add_f32_e32 v90, v99, v90
	v_add_f32_e32 v90, v97, v90
	v_add_f32_e32 v90, v96, v90
	v_add_f32_e32 v90, v172, v90
	v_add_f32_e32 v90, v101, v90
	v_cndmask_b32_e64 v93, v91, 0, s[70:71]
	v_add_f32_e32 v90, v94, v90
	v_add_f32_e32 v184, v93, v90
	v_cvt_pk_bf16_f32 v90, v100, v99
	v_cvt_pk_bf16_f32 v91, v97, v96
	v_cvt_pk_bf16_f32 v92, v172, v101
	v_cvt_pk_bf16_f32 v93, v94, v93
	ds_read_b128 v[94:97], v152 offset:26112
	ds_read_b128 v[98:101], v152 offset:27200
	ds_read_b128 v[186:189], v152 offset:26176
	ds_read_b128 v[190:193], v152 offset:27264
	s_waitcnt lgkmcnt(3)
	v_mfma_f32_16x16x32_bf16 v[94:97], v[94:97], v[78:81], 0
	s_waitcnt lgkmcnt(2)
	v_mfma_f32_16x16x32_bf16 v[98:101], v[98:101], v[78:81], 0
	s_waitcnt lgkmcnt(1)
	v_mfma_f32_16x16x32_bf16 v[94:97], v[186:189], v[74:77], v[94:97]
	s_waitcnt lgkmcnt(0)
	v_mfma_f32_16x16x32_bf16 v[98:101], v[190:193], v[74:77], v[98:101]
	ds_read_b128 v[186:189], v152 offset:26240
	ds_read_b128 v[190:193], v152 offset:27328
	s_waitcnt lgkmcnt(1)
	v_mfma_f32_16x16x32_bf16 v[94:97], v[186:189], v[70:73], v[94:97]
	s_waitcnt lgkmcnt(0)
	v_mfma_f32_16x16x32_bf16 v[186:189], v[190:193], v[70:73], v[98:101]
	s_nop 2
	ds_read_b128 v[98:101], v152 offset:26304
	ds_read_b128 v[190:193], v152 offset:27392
	s_waitcnt lgkmcnt(1)
	v_mfma_f32_16x16x32_bf16 v[98:101], v[98:101], v[66:69], v[94:97]
	s_waitcnt lgkmcnt(0)
	v_mfma_f32_16x16x32_bf16 v[94:97], v[190:193], v[66:69], v[186:189]
	s_nop 2
	ds_read_b128 v[186:189], v142 offset:384
	ds_read_b128 v[190:193], v142 offset:400
	s_waitcnt lgkmcnt(1)
	v_sub_f32_e32 v172, v186, v182
	v_mul_f32_e32 v172, 0x3fb8aa3b, v172
	v_exp_f32_e32 v186, v172
	s_waitcnt lgkmcnt(0)
	v_sub_f32_e32 v172, v190, v182
	v_mul_f32_e32 v172, 0x3fb8aa3b, v172
	v_exp_f32_e32 v190, v172
	v_sub_f32_e32 v172, v187, v182
	v_mul_f32_e32 v172, 0x3fb8aa3b, v172
	v_exp_f32_e32 v187, v172
	s_nop 0
	v_pk_mul_f32 v[98:99], v[98:99], v[186:187]
	s_nop 0
	v_cndmask_b32_e64 v173, v98, 0, s[76:77]
	v_sub_f32_e32 v98, v191, v182
	v_mul_f32_e32 v98, 0x3fb8aa3b, v98
	v_exp_f32_e32 v191, v98
	v_cndmask_b32_e64 v172, v99, 0, s[74:75]
	v_pk_mul_f32 v[94:95], v[94:95], v[190:191]
	s_nop 0
	v_cndmask_b32_e64 v190, v95, 0, s[78:79]
	v_sub_f32_e32 v95, v192, v182
	v_mul_f32_e32 v95, 0x3fb8aa3b, v95
	v_cndmask_b32_e64 v194, v94, 0, s[80:81]
	v_sub_f32_e32 v94, v188, v182
	v_exp_f32_e32 v98, v95
	v_sub_f32_e32 v95, v189, v182
	v_mul_f32_e32 v94, 0x3fb8aa3b, v94
	v_mul_f32_e32 v95, 0x3fb8aa3b, v95
	v_exp_f32_e32 v94, v94
	v_exp_f32_e32 v95, v95
	s_nop 0
	v_pk_mul_f32 v[94:95], v[100:101], v[94:95]
	s_nop 0
	v_cndmask_b32_e64 v101, v94, 0, s[84:85]
	v_sub_f32_e32 v94, v193, v182
	v_mul_f32_e32 v94, 0x3fb8aa3b, v94
	v_exp_f32_e32 v99, v94
	v_cndmask_b32_e64 v100, v95, 0, s[82:83]
	v_pk_mul_f32 v[94:95], v[96:97], v[98:99]
	s_nop 0
	v_cndmask_b32_e64 v192, v94, 0, s[88:89]
	v_add_f32_e32 v94, v184, v173
	v_add_f32_e32 v94, v172, v94
	v_add_f32_e32 v94, v101, v94
	v_add_u32_e32 v98, 0, v141
	v_add_f32_e32 v196, v100, v94
	v_cvt_pk_bf16_f32 v94, v173, v172
	v_add_u32_e32 v172, 0x22600, v98
	v_cndmask_b32_e64 v188, v95, 0, s[86:87]
	v_cvt_pk_bf16_f32 v95, v101, v100
	ds_read_b128 v[98:101], v172
	ds_read_b128 v[184:187], v172 offset:16
	v_cvt_pk_bf16_f32 v97, v192, v188
	v_cvt_pk_bf16_f32 v96, v194, v190
	s_waitcnt lgkmcnt(1)
	v_pk_mul_f32 v[98:99], v[98:99], v[198:199]
	v_and_b32_e32 v199, 0xffff0000, v79
	v_lshlrev_b32_e32 v198, 16, v79
	v_pk_mul_f32 v[100:101], v[100:101], v[198:199]
	v_add_f32_e32 v98, v98, v99
	v_add_f32_e32 v98, v100, v98
	v_add_f32_e32 v98, v101, v98
	v_add_f32_e32 v173, 0, v98
	ds_read_b128 v[98:101], v172 offset:128
	v_lshlrev_b32_e32 v199, 16, v74
	v_lshlrev_b32_e32 v198, 16, v80
	s_waitcnt lgkmcnt(1)
	v_mov_b32_e32 v200, v184
	v_lshlrev_b32_e32 v184, 16, v81
	s_waitcnt lgkmcnt(0)
	v_mov_b32_e32 v201, v98
	v_mov_b32_e32 v98, v185
	v_pk_mul_f32 v[98:99], v[98:99], v[230:231]
	v_lshlrev_b32_e32 v185, 16, v75
	v_pk_fma_f32 v[98:99], v[200:201], v[198:199], v[98:99]
	v_mov_b32_e32 v198, v186
	v_mov_b32_e32 v199, v100
	v_pk_fma_f32 v[98:99], v[198:199], v[184:185], v[98:99]
	v_and_b32_e32 v185, 0xffff0000, v75
	v_and_b32_e32 v184, 0xffff0000, v81
	v_mov_b32_e32 v100, v187
	v_pk_fma_f32 v[98:99], v[100:101], v[184:185], v[98:99]
	v_and_b32_e32 v231, 0xffff0000, v70
	v_add_f32_e32 v98, v173, v98
	v_add_f32_e32 v173, v98, v99
	ds_read_b128 v[98:101], v172 offset:144
	ds_read_b128 v[184:187], v172 offset:256
	v_and_b32_e32 v230, 0xffff0000, v76
	v_lshlrev_b32_e32 v199, 16, v70
	v_lshlrev_b32_e32 v198, 16, v76
	s_waitcnt lgkmcnt(1)
	v_mov_b32_e32 v200, v98
	s_waitcnt lgkmcnt(0)
	v_mov_b32_e32 v201, v184
	v_mov_b32_e32 v184, v99
	v_pk_mul_f32 v[98:99], v[184:185], v[230:231]
	v_lshlrev_b32_e32 v185, 16, v71
	v_pk_fma_f32 v[98:99], v[200:201], v[198:199], v[98:99]
	v_lshlrev_b32_e32 v184, 16, v77
	v_mov_b32_e32 v198, v100
	v_mov_b32_e32 v199, v186
	v_pk_fma_f32 v[98:99], v[198:199], v[184:185], v[98:99]
	v_and_b32_e32 v185, 0xffff0000, v71
	v_and_b32_e32 v184, 0xffff0000, v77
	v_mov_b32_e32 v186, v101
	v_pk_fma_f32 v[98:99], v[186:187], v[184:185], v[98:99]
	v_and_b32_e32 v231, 0xffff0000, v66
	v_add_f32_e32 v98, v173, v98
	v_add_f32_e32 v173, v98, v99
	ds_read_b128 v[98:101], v172 offset:272
	ds_read_b128 v[184:187], v172 offset:384
	v_and_b32_e32 v230, 0xffff0000, v72
	v_lshlrev_b32_e32 v199, 16, v66
	v_lshlrev_b32_e32 v198, 16, v72
	s_waitcnt lgkmcnt(1)
	v_mov_b32_e32 v200, v98
	s_waitcnt lgkmcnt(0)
	v_mov_b32_e32 v201, v184
	v_mov_b32_e32 v184, v99
	v_pk_mul_f32 v[98:99], v[184:185], v[230:231]
	v_lshlrev_b32_e32 v185, 16, v67
	v_pk_fma_f32 v[98:99], v[200:201], v[198:199], v[98:99]
	v_lshlrev_b32_e32 v184, 16, v73
	v_mov_b32_e32 v198, v100
	v_mov_b32_e32 v199, v186
	v_pk_fma_f32 v[98:99], v[198:199], v[184:185], v[98:99]
	v_and_b32_e32 v185, 0xffff0000, v67
	v_and_b32_e32 v184, 0xffff0000, v73
	v_mov_b32_e32 v186, v101
	v_pk_fma_f32 v[98:99], v[186:187], v[184:185], v[98:99]
	s_load_dwordx2 s[16:17], s[16:17], 0x118
	v_add_f32_e32 v98, v173, v98
	v_add_f32_e32 v189, v98, v99
	ds_read_b128 v[98:101], v172 offset:400
	v_lshlrev_b32_e32 v172, 16, v68
	s_waitcnt lgkmcnt(0)
	v_lshl_add_u64 v[134:135], s[16:17], 0, v[134:135]
	s_mov_b64 s[16:17], 0x2134200
	v_lshl_add_u64 v[134:135], v[134:135], 0, s[16:17]
	v_mul_f32_e32 v195, v98, v172
	v_and_b32_e32 v98, 0xffff0000, v68
	v_mul_f32_e32 v197, v99, v98
	v_lshlrev_b32_e32 v98, 16, v69
	v_mul_f32_e32 v191, v100, v98
	v_and_b32_e32 v98, 0xffff0000, v69
	v_mul_f32_e32 v193, v101, v98
	v_pk_add_f32 v[100:101], v[194:195], v[196:197]
	ds_read_b32 v99, v145
	v_pk_add_f32 v[100:101], v[190:191], v[100:101]
	v_exp_f32_e32 v98, v183
	v_pk_add_f32 v[100:101], v[192:193], v[100:101]
	v_readlane_b32 s16, v254, 60
	v_pk_add_f32 v[100:101], v[188:189], v[100:101]
	ds_bpermute_b32 v184, v143, v100
	ds_bpermute_b32 v185, v143, v101
	ds_read_b128 v[186:189], v169 offset:64
	s_waitcnt lgkmcnt(3)
	v_add_f32_e32 v99, v182, v99
	v_mul_f32_e32 v99, 0xbfb8aa3b, v99
	v_exp_f32_e32 v99, v99
	s_waitcnt lgkmcnt(1)
	v_pk_add_f32 v[100:101], v[100:101], v[184:185]
	ds_bpermute_b32 v184, v144, v100
	ds_bpermute_b32 v185, v144, v101
	v_readlane_b32 s17, v254, 61
	s_waitcnt lgkmcnt(0)
	v_pk_add_f32 v[100:101], v[100:101], v[184:185]
	s_waitcnt lgkmcnt(0)
	ds_read_b128 v[234:237], v169
	ds_read_b128 v[238:241], v169 offset:128
	ds_read_b128 v[242:245], v169 offset:192
	ds_read_b128 v[246:249], v176
	ds_read_b128 v[250:253], v176 offset:64
	s_nop 0
	s_waitcnt lgkmcnt(4)
	v_mfma_f32_16x16x32_bf16 v[182:185], v[234:237], v[78:81], 0
	ds_read_b128 v[234:237], v176 offset:128
	v_fmac_f32_e32 v100, v98, v101
	v_max_f32_e64 v99, |v100|, v99
	v_div_scale_f32 v100, s[90:91], v99, v99, 1.0
	v_mfma_f32_16x16x32_bf16 v[182:185], v[186:189], v[74:77], v[182:185]
	s_nop 0
	v_rcp_f32_e32 v101, v100
	v_lshl_add_u64 v[132:133], s[16:17], 0, v[132:133]
	s_nop 0
	s_waitcnt lgkmcnt(4)
	v_mfma_f32_16x16x32_bf16 v[182:185], v[238:241], v[70:73], v[182:185]
	s_nop 0
	ds_read_b128 v[238:241], v176 offset:192
	v_fma_f32 v172, -v100, v101, 1.0
	v_fmac_f32_e32 v101, v172, v101
	s_nop 0
	s_waitcnt lgkmcnt(4)
	v_mfma_f32_16x16x32_bf16 v[182:185], v[242:245], v[66:69], v[182:185]
	s_nop 0
	ds_read_b128 v[242:245], v169 offset:4416
	v_div_scale_f32 v172, vcc, 1.0, v99, 1.0
	s_nop 5
	v_pk_mul_f32 v[184:185], v[98:99], v[184:185] op_sel_hi:[0,1]
	v_pk_mul_f32 v[182:183], v[98:99], v[182:183] op_sel_hi:[0,1]
	v_mul_f32_e32 v173, v172, v101
	v_fma_f32 v174, -v100, v173, v172
	s_nop 0
	s_waitcnt lgkmcnt(4)
	v_mfma_f32_16x16x32_bf16 v[182:185], v[246:249], v[82:85], v[182:185]
	s_nop 0
	ds_read_b128 v[246:249], v169 offset:4352
	v_fmac_f32_e32 v173, v174, v101
	v_fma_f32 v100, -v100, v173, v172
	s_nop 0
	s_waitcnt lgkmcnt(4)
	v_mfma_f32_16x16x32_bf16 v[182:185], v[250:253], v[86:89], v[182:185]
	s_nop 0
	ds_read_b128 v[250:253], v169 offset:4480
	v_div_fmas_f32 v100, v100, v101, v173
	v_readlane_b32 s90, v254, 19
	s_nop 0
	s_waitcnt lgkmcnt(4)
	v_mfma_f32_16x16x32_bf16 v[182:185], v[234:237], v[90:93], v[182:185]
	s_nop 0
	ds_read_b128 v[234:237], v169 offset:4544
	v_div_fixup_f32 v100, v100, v99, 1.0
	v_cndmask_b32_e64 v133, v133, v135, s[6:7]
	s_nop 0
	s_waitcnt lgkmcnt(4)
	v_mfma_f32_16x16x32_bf16 v[182:185], v[238:241], v[94:97], v[182:185]
	ds_read_b128 v[238:241], v176 offset:4352
	v_cndmask_b32_e64 v132, v132, v134, s[6:7]
	v_readlane_b32 s91, v254, 20
	s_nop 0
	s_nop 4
	v_pk_mul_f32 v[134:135], v[100:101], v[184:185] op_sel_hi:[0,1]
	v_lshl_add_u64 v[132:133], v[132:133], 0, s[90:91]
	v_pk_mul_f32 v[182:183], v[100:101], v[182:183] op_sel_hi:[0,1]
	v_lshl_add_u64 v[132:133], v[132:133], 0, v[0:1]
	v_cvt_pk_bf16_f32 v182, v182, v183
	v_cvt_pk_bf16_f32 v183, v134, v135
	global_store_dwordx2 v[132:133], v[182:183], off
	s_nop 0
	s_nop 0
	s_waitcnt lgkmcnt(3)
	v_mfma_f32_16x16x32_bf16 v[182:185], v[246:249], v[78:81], 0
	ds_read_b128 v[246:249], v176 offset:4416
	v_mfma_f32_16x16x32_bf16 v[182:185], v[242:245], v[74:77], v[182:185]
	s_nop 0
	ds_read_b128 v[242:245], v176 offset:4480
	s_nop 0
	s_waitcnt lgkmcnt(4)
	v_mfma_f32_16x16x32_bf16 v[182:185], v[250:253], v[70:73], v[182:185]
	s_nop 0
	ds_read_b128 v[250:253], v176 offset:4544
	s_nop 0
	s_waitcnt lgkmcnt(4)
	v_mfma_f32_16x16x32_bf16 v[182:185], v[234:237], v[66:69], v[182:185]
	s_nop 0
	ds_read_b128 v[234:237], v169 offset:8768
	s_nop 6
	v_pk_mul_f32 v[184:185], v[98:99], v[184:185] op_sel_hi:[0,1]
	v_pk_mul_f32 v[182:183], v[98:99], v[182:183] op_sel_hi:[0,1]
	s_nop 0
	s_nop 0
	s_waitcnt lgkmcnt(4)
	v_mfma_f32_16x16x32_bf16 v[182:185], v[238:241], v[82:85], v[182:185]
	s_nop 0
	ds_read_b128 v[238:241], v169 offset:8704
	s_nop 0
	s_waitcnt lgkmcnt(4)
	v_mfma_f32_16x16x32_bf16 v[182:185], v[246:249], v[86:89], v[182:185]
	s_nop 0
	ds_read_b128 v[246:249], v169 offset:8832
	s_nop 0
	s_waitcnt lgkmcnt(4)
	v_mfma_f32_16x16x32_bf16 v[182:185], v[242:245], v[90:93], v[182:185]
	s_nop 0
	ds_read_b128 v[242:245], v169 offset:8896
	s_nop 0
	s_waitcnt lgkmcnt(4)
	v_mfma_f32_16x16x32_bf16 v[182:185], v[250:253], v[94:97], v[182:185]
	s_nop 0
	ds_read_b128 v[250:253], v176 offset:8704
	s_nop 6
	v_pk_mul_f32 v[134:135], v[100:101], v[184:185] op_sel_hi:[0,1]
	v_pk_mul_f32 v[182:183], v[100:101], v[182:183] op_sel_hi:[0,1]
	v_cvt_pk_bf16_f32 v182, v182, v183
	v_cvt_pk_bf16_f32 v183, v134, v135
	global_store_dwordx2 v[132:133], v[182:183], off offset:32
	s_nop 0
	s_nop 0
	s_waitcnt lgkmcnt(3)
	v_mfma_f32_16x16x32_bf16 v[182:185], v[238:241], v[78:81], 0
	ds_read_b128 v[238:241], v176 offset:8768
	v_mfma_f32_16x16x32_bf16 v[182:185], v[234:237], v[74:77], v[182:185]
	s_nop 0
	ds_read_b128 v[234:237], v176 offset:8832
	s_nop 0
	s_waitcnt lgkmcnt(4)
	v_mfma_f32_16x16x32_bf16 v[182:185], v[246:249], v[70:73], v[182:185]
	s_nop 0
	ds_read_b128 v[246:249], v176 offset:8896
	s_nop 0
	s_waitcnt lgkmcnt(4)
	v_mfma_f32_16x16x32_bf16 v[182:185], v[242:245], v[66:69], v[182:185]
	s_nop 0
	ds_read_b128 v[242:245], v169 offset:13120
	s_nop 6
	v_pk_mul_f32 v[184:185], v[98:99], v[184:185] op_sel_hi:[0,1]
	v_pk_mul_f32 v[182:183], v[98:99], v[182:183] op_sel_hi:[0,1]
	s_nop 0
	s_nop 0
	s_waitcnt lgkmcnt(4)
	v_mfma_f32_16x16x32_bf16 v[182:185], v[250:253], v[82:85], v[182:185]
	s_nop 0
	ds_read_b128 v[250:253], v169 offset:13056
	s_nop 0
	s_waitcnt lgkmcnt(4)
	v_mfma_f32_16x16x32_bf16 v[182:185], v[238:241], v[86:89], v[182:185]
	s_nop 0
	ds_read_b128 v[238:241], v169 offset:13184
	s_nop 0
	s_waitcnt lgkmcnt(4)
	v_mfma_f32_16x16x32_bf16 v[182:185], v[234:237], v[90:93], v[182:185]
	s_nop 0
	ds_read_b128 v[234:237], v169 offset:13248
	s_nop 0
	s_waitcnt lgkmcnt(4)
	v_mfma_f32_16x16x32_bf16 v[182:185], v[246:249], v[94:97], v[182:185]
	s_nop 0
	ds_read_b128 v[246:249], v176 offset:13056
	s_nop 6
	v_pk_mul_f32 v[134:135], v[100:101], v[184:185] op_sel_hi:[0,1]
	v_pk_mul_f32 v[182:183], v[100:101], v[182:183] op_sel_hi:[0,1]
	v_cvt_pk_bf16_f32 v182, v182, v183
	v_cvt_pk_bf16_f32 v183, v134, v135
	global_store_dwordx2 v[132:133], v[182:183], off offset:64
	s_nop 0
	s_nop 0
	s_waitcnt lgkmcnt(3)
	v_mfma_f32_16x16x32_bf16 v[182:185], v[250:253], v[78:81], 0
	ds_read_b128 v[250:253], v176 offset:13120
	v_mfma_f32_16x16x32_bf16 v[182:185], v[242:245], v[74:77], v[182:185]
	s_nop 0
	ds_read_b128 v[242:245], v176 offset:13184
	s_nop 0
	s_waitcnt lgkmcnt(4)
	v_mfma_f32_16x16x32_bf16 v[182:185], v[238:241], v[70:73], v[182:185]
	s_nop 0
	ds_read_b128 v[238:241], v176 offset:13248
	s_nop 0
	s_waitcnt lgkmcnt(4)
	v_mfma_f32_16x16x32_bf16 v[182:185], v[234:237], v[66:69], v[182:185]
	s_nop 0
	ds_read_b128 v[234:237], v169 offset:17472
	s_nop 6
	v_pk_mul_f32 v[184:185], v[98:99], v[184:185] op_sel_hi:[0,1]
	v_pk_mul_f32 v[182:183], v[98:99], v[182:183] op_sel_hi:[0,1]
	s_nop 0
	s_nop 0
	s_waitcnt lgkmcnt(4)
	v_mfma_f32_16x16x32_bf16 v[182:185], v[246:249], v[82:85], v[182:185]
	s_nop 0
	ds_read_b128 v[246:249], v169 offset:17408
	s_nop 0
	s_waitcnt lgkmcnt(4)
	v_mfma_f32_16x16x32_bf16 v[182:185], v[250:253], v[86:89], v[182:185]
	s_nop 0
	ds_read_b128 v[250:253], v169 offset:17536
	s_nop 0
	s_waitcnt lgkmcnt(4)
	v_mfma_f32_16x16x32_bf16 v[182:185], v[242:245], v[90:93], v[182:185]
	s_nop 0
	ds_read_b128 v[242:245], v169 offset:17600
	s_nop 0
	s_waitcnt lgkmcnt(4)
	v_mfma_f32_16x16x32_bf16 v[182:185], v[238:241], v[94:97], v[182:185]
	s_nop 0
	ds_read_b128 v[238:241], v176 offset:17408
	s_nop 6
	v_pk_mul_f32 v[134:135], v[100:101], v[184:185] op_sel_hi:[0,1]
	v_pk_mul_f32 v[182:183], v[100:101], v[182:183] op_sel_hi:[0,1]
	v_cvt_pk_bf16_f32 v182, v182, v183
	v_cvt_pk_bf16_f32 v183, v134, v135
	global_store_dwordx2 v[132:133], v[182:183], off offset:96
	s_nop 0
	s_nop 0
	s_waitcnt lgkmcnt(3)
	v_mfma_f32_16x16x32_bf16 v[182:185], v[246:249], v[78:81], 0
	ds_read_b128 v[246:249], v176 offset:17472
	v_mfma_f32_16x16x32_bf16 v[182:185], v[234:237], v[74:77], v[182:185]
	s_nop 0
	ds_read_b128 v[234:237], v176 offset:17536
	s_nop 0
	s_waitcnt lgkmcnt(4)
	v_mfma_f32_16x16x32_bf16 v[182:185], v[250:253], v[70:73], v[182:185]
	s_nop 0
	ds_read_b128 v[250:253], v176 offset:17600
	s_nop 0
	s_waitcnt lgkmcnt(4)
	v_mfma_f32_16x16x32_bf16 v[182:185], v[242:245], v[66:69], v[182:185]
	s_nop 0
	ds_read_b128 v[242:245], v169 offset:21824
	s_nop 6
	v_pk_mul_f32 v[184:185], v[98:99], v[184:185] op_sel_hi:[0,1]
	v_pk_mul_f32 v[182:183], v[98:99], v[182:183] op_sel_hi:[0,1]
	s_nop 0
	s_nop 0
	s_waitcnt lgkmcnt(4)
	v_mfma_f32_16x16x32_bf16 v[182:185], v[238:241], v[82:85], v[182:185]
	s_nop 0
	ds_read_b128 v[238:241], v169 offset:21760
	s_nop 0
	s_waitcnt lgkmcnt(4)
	v_mfma_f32_16x16x32_bf16 v[182:185], v[246:249], v[86:89], v[182:185]
	s_nop 0
	ds_read_b128 v[246:249], v169 offset:21888
	s_nop 0
	s_waitcnt lgkmcnt(4)
	v_mfma_f32_16x16x32_bf16 v[182:185], v[234:237], v[90:93], v[182:185]
	s_nop 0
	ds_read_b128 v[234:237], v169 offset:21952
	s_nop 0
	s_waitcnt lgkmcnt(4)
	v_mfma_f32_16x16x32_bf16 v[182:185], v[250:253], v[94:97], v[182:185]
	s_nop 0
	ds_read_b128 v[250:253], v176 offset:21760
	s_nop 6
	v_pk_mul_f32 v[134:135], v[100:101], v[184:185] op_sel_hi:[0,1]
	v_pk_mul_f32 v[182:183], v[100:101], v[182:183] op_sel_hi:[0,1]
	v_cvt_pk_bf16_f32 v182, v182, v183
	v_cvt_pk_bf16_f32 v183, v134, v135
	global_store_dwordx2 v[132:133], v[182:183], off offset:128
	s_nop 0
	s_nop 0
	s_waitcnt lgkmcnt(3)
	v_mfma_f32_16x16x32_bf16 v[182:185], v[238:241], v[78:81], 0
	ds_read_b128 v[238:241], v176 offset:21824
	v_mfma_f32_16x16x32_bf16 v[182:185], v[242:245], v[74:77], v[182:185]
	s_nop 0
	ds_read_b128 v[242:245], v176 offset:21888
	s_nop 0
	s_waitcnt lgkmcnt(4)
	v_mfma_f32_16x16x32_bf16 v[182:185], v[246:249], v[70:73], v[182:185]
	s_nop 0
	ds_read_b128 v[246:249], v176 offset:21952
	s_nop 0
	s_waitcnt lgkmcnt(4)
	v_mfma_f32_16x16x32_bf16 v[182:185], v[234:237], v[66:69], v[182:185]
	s_nop 0
	ds_read_b128 v[234:237], v169 offset:26176
	s_nop 6
	v_pk_mul_f32 v[184:185], v[98:99], v[184:185] op_sel_hi:[0,1]
	v_pk_mul_f32 v[182:183], v[98:99], v[182:183] op_sel_hi:[0,1]
	s_nop 0
	s_nop 0
	s_waitcnt lgkmcnt(4)
	v_mfma_f32_16x16x32_bf16 v[182:185], v[250:253], v[82:85], v[182:185]
	s_nop 0
	ds_read_b128 v[250:253], v169 offset:26112
	s_nop 0
	s_waitcnt lgkmcnt(4)
	v_mfma_f32_16x16x32_bf16 v[182:185], v[238:241], v[86:89], v[182:185]
	s_nop 0
	ds_read_b128 v[238:241], v169 offset:26240
	s_nop 0
	s_waitcnt lgkmcnt(4)
	v_mfma_f32_16x16x32_bf16 v[182:185], v[242:245], v[90:93], v[182:185]
	s_nop 0
	ds_read_b128 v[242:245], v169 offset:26304
	s_nop 0
	s_waitcnt lgkmcnt(4)
	v_mfma_f32_16x16x32_bf16 v[182:185], v[246:249], v[94:97], v[182:185]
	s_nop 0
	ds_read_b128 v[246:249], v176 offset:26112
	s_nop 6
	v_pk_mul_f32 v[134:135], v[100:101], v[184:185] op_sel_hi:[0,1]
	v_pk_mul_f32 v[182:183], v[100:101], v[182:183] op_sel_hi:[0,1]
	v_cvt_pk_bf16_f32 v182, v182, v183
	v_cvt_pk_bf16_f32 v183, v134, v135
	global_store_dwordx2 v[132:133], v[182:183], off offset:160
	s_nop 0
	s_nop 0
	s_waitcnt lgkmcnt(3)
	v_mfma_f32_16x16x32_bf16 v[182:185], v[250:253], v[78:81], 0
	ds_read_b128 v[250:253], v176 offset:26176
	v_mfma_f32_16x16x32_bf16 v[182:185], v[234:237], v[74:77], v[182:185]
	s_nop 0
	ds_read_b128 v[234:237], v176 offset:26240
	s_nop 0
	s_waitcnt lgkmcnt(4)
	v_mfma_f32_16x16x32_bf16 v[182:185], v[238:241], v[70:73], v[182:185]
	s_nop 0
	ds_read_b128 v[238:241], v169 offset:30464
	s_nop 0
	s_waitcnt lgkmcnt(4)
	v_mfma_f32_16x16x32_bf16 v[182:185], v[242:245], v[66:69], v[182:185]
	s_nop 0
	s_nop 6
	v_pk_mul_f32 v[184:185], v[98:99], v[184:185] op_sel_hi:[0,1]
	v_pk_mul_f32 v[182:183], v[98:99], v[182:183] op_sel_hi:[0,1]
	s_nop 0
	s_nop 0
	s_waitcnt lgkmcnt(3)
	v_mfma_f32_16x16x32_bf16 v[182:185], v[246:249], v[82:85], v[182:185]
	s_nop 0
	ds_read_b128 v[242:245], v169 offset:30592
	s_nop 0
	s_waitcnt lgkmcnt(3)
	v_mfma_f32_16x16x32_bf16 v[182:185], v[250:253], v[86:89], v[182:185]
	s_nop 0
	ds_read_b128 v[246:249], v169 offset:30656
	s_nop 0
	s_waitcnt lgkmcnt(3)
	v_mfma_f32_16x16x32_bf16 v[182:185], v[234:237], v[90:93], v[182:185]
	ds_read_b128 v[234:237], v176 offset:30464
	ds_read_b128 v[186:189], v176 offset:26304
	s_nop 0
	s_waitcnt lgkmcnt(0)
	v_mfma_f32_16x16x32_bf16 v[182:185], v[186:189], v[94:97], v[182:185]
	s_nop 7
	v_pk_mul_f32 v[134:135], v[100:101], v[184:185] op_sel_hi:[0,1]
	v_pk_mul_f32 v[182:183], v[100:101], v[182:183] op_sel_hi:[0,1]
	v_cvt_pk_bf16_f32 v182, v182, v183
	v_cvt_pk_bf16_f32 v183, v134, v135
	global_store_dwordx2 v[132:133], v[182:183], off offset:192
	s_nop 0
	ds_read_b128 v[250:253], v176 offset:30528
	s_nop 0
	v_mfma_f32_16x16x32_bf16 v[78:81], v[238:241], v[78:81], 0
	ds_read_b128 v[238:241], v176 offset:30592
	ds_read_b128 v[182:185], v169 offset:30528
	s_nop 0
	s_waitcnt lgkmcnt(0)
	v_mfma_f32_16x16x32_bf16 v[74:77], v[182:185], v[74:77], v[78:81]
	s_nop 4
	s_nop 0
	s_nop 0
	v_mfma_f32_16x16x32_bf16 v[70:73], v[242:245], v[70:73], v[74:77]
	ds_read_b128 v[242:245], v176 offset:30656
	s_nop 2
	s_nop 0
	s_nop 0
	v_mfma_f32_16x16x32_bf16 v[66:69], v[246:249], v[66:69], v[70:73]
	s_nop 2
	s_nop 0
	s_nop 3
	v_pk_mul_f32 v[68:69], v[98:99], v[68:69] op_sel_hi:[0,1]
	v_pk_mul_f32 v[66:67], v[98:99], v[66:67] op_sel_hi:[0,1]
	s_nop 0
	s_nop 0
	v_mfma_f32_16x16x32_bf16 v[66:69], v[234:237], v[82:85], v[66:69]
	s_nop 0
	s_nop 0
	v_mfma_f32_16x16x32_bf16 v[66:69], v[250:253], v[86:89], v[66:69]
	s_nop 0
	s_nop 0
	v_mfma_f32_16x16x32_bf16 v[66:69], v[238:241], v[90:93], v[66:69]
	s_nop 0
	ds_read_b128 v[234:237], v178 offset:34816
	s_nop 0
	s_waitcnt lgkmcnt(1)
	v_mfma_f32_16x16x32_bf16 v[66:69], v[242:245], v[94:97], v[66:69]
	s_nop 7
	v_pk_mul_f32 v[68:69], v[100:101], v[68:69] op_sel_hi:[0,1]
	v_pk_mul_f32 v[66:67], v[100:101], v[66:67] op_sel_hi:[0,1]
	v_cvt_pk_bf16_f32 v66, v66, v67
	v_cvt_pk_bf16_f32 v67, v68, v69
	global_store_dwordx2 v[132:133], v[66:67], off offset:224
	v_sub_f32_e32 v66, v181, v179
	v_mul_f32_e32 v82, 0x3fb8aa3b, v66
	ds_read_b128 v[238:241], v178 offset:34880
	ds_read_b128 v[78:81], v177
	ds_read_b128 v[242:245], v178 offset:34944
	ds_read_b128 v[74:77], v177 offset:64
	ds_read_b128 v[246:249], v178 offset:35008
	ds_read_b128 v[70:73], v177 offset:128
	ds_read_b128 v[250:253], v178 offset:39168
	ds_read_b128 v[66:69], v177 offset:192
	v_exp_f32_e32 v82, v82
	s_nop 0
	v_pk_mul_f32 v[48:49], v[48:49], v[82:83] op_sel_hi:[1,0]
	v_pk_mul_f32 v[46:47], v[46:47], v[82:83] op_sel_hi:[1,0]
	v_pk_mul_f32 v[64:65], v[64:65], v[82:83] op_sel_hi:[1,0]
	v_pk_mul_f32 v[62:63], v[62:63], v[82:83] op_sel_hi:[1,0]
	s_nop 0
	s_waitcnt lgkmcnt(6)
	v_mfma_f32_16x16x32_bf16 v[46:49], v[78:81], v[234:237], v[46:49]
	s_nop 0
	ds_read_b128 v[234:237], v178 offset:39232
	v_pk_mul_f32 v[60:61], v[60:61], v[82:83] op_sel_hi:[1,0]
	v_pk_mul_f32 v[58:59], v[58:59], v[82:83] op_sel_hi:[1,0]
	s_nop 0
	s_waitcnt lgkmcnt(5)
	v_mfma_f32_16x16x32_bf16 v[46:49], v[74:77], v[238:241], v[46:49]
	s_nop 0
	ds_read_b128 v[238:241], v178 offset:39296
	v_pk_mul_f32 v[52:53], v[52:53], v[82:83] op_sel_hi:[1,0]
	v_pk_mul_f32 v[50:51], v[50:51], v[82:83] op_sel_hi:[1,0]
	s_nop 0
	s_waitcnt lgkmcnt(4)
	v_mfma_f32_16x16x32_bf16 v[46:49], v[70:73], v[242:245], v[46:49]
	s_nop 0
	ds_read_b128 v[242:245], v178 offset:39360
	v_pk_mul_f32 v[44:45], v[44:45], v[82:83] op_sel_hi:[1,0]
	v_pk_mul_f32 v[42:43], v[42:43], v[82:83] op_sel_hi:[1,0]
	s_nop 0
	s_waitcnt lgkmcnt(3)
	v_mfma_f32_16x16x32_bf16 v[46:49], v[66:69], v[246:249], v[46:49]
	s_nop 0
	ds_read_b128 v[246:249], v178 offset:43520
	v_pk_mul_f32 v[40:41], v[40:41], v[82:83] op_sel_hi:[1,0]
	v_pk_mul_f32 v[38:39], v[38:39], v[82:83] op_sel_hi:[1,0]
	s_nop 0
	v_mfma_f32_16x16x32_bf16 v[62:65], v[78:81], v[250:253], v[62:65]
	s_nop 0
	ds_read_b128 v[250:253], v178 offset:43584
	v_pk_mul_f32 v[36:37], v[36:37], v[82:83] op_sel_hi:[1,0]
	v_pk_mul_f32 v[34:35], v[34:35], v[82:83] op_sel_hi:[1,0]
	s_nop 0
	s_waitcnt lgkmcnt(4)
	v_mfma_f32_16x16x32_bf16 v[62:65], v[74:77], v[234:237], v[62:65]
	s_nop 0
	ds_read_b128 v[234:237], v178 offset:43648
	v_pk_mul_f32 v[56:57], v[56:57], v[82:83] op_sel_hi:[1,0]
	v_pk_mul_f32 v[54:55], v[54:55], v[82:83] op_sel_hi:[1,0]
	s_nop 0
	s_waitcnt lgkmcnt(4)
	v_mfma_f32_16x16x32_bf16 v[62:65], v[70:73], v[238:241], v[62:65]
	s_nop 0
	ds_read_b128 v[238:241], v178 offset:43712
	s_nop 0
	s_waitcnt lgkmcnt(4)
	v_mfma_f32_16x16x32_bf16 v[62:65], v[66:69], v[242:245], v[62:65]
	s_nop 0
	ds_read_b128 v[242:245], v178 offset:47872
	s_nop 0
	s_waitcnt lgkmcnt(4)
	v_mfma_f32_16x16x32_bf16 v[58:61], v[78:81], v[246:249], v[58:61]
	s_nop 0
	ds_read_b128 v[246:249], v178 offset:47936
	s_nop 0
	s_waitcnt lgkmcnt(4)
	v_mfma_f32_16x16x32_bf16 v[58:61], v[74:77], v[250:253], v[58:61]
	s_nop 0
	ds_read_b128 v[250:253], v178 offset:48000
	s_nop 0
	s_waitcnt lgkmcnt(4)
	v_mfma_f32_16x16x32_bf16 v[58:61], v[70:73], v[234:237], v[58:61]
	s_nop 0
	ds_read_b128 v[234:237], v178 offset:48064
	s_nop 0
	s_waitcnt lgkmcnt(4)
	v_mfma_f32_16x16x32_bf16 v[58:61], v[66:69], v[238:241], v[58:61]
	s_nop 0
	ds_read_b128 v[238:241], v178 offset:52224
	s_nop 0
	s_waitcnt lgkmcnt(4)
	v_mfma_f32_16x16x32_bf16 v[50:53], v[78:81], v[242:245], v[50:53]
	s_nop 0
	ds_read_b128 v[242:245], v178 offset:52288
	s_nop 0
	s_waitcnt lgkmcnt(4)
	v_mfma_f32_16x16x32_bf16 v[50:53], v[74:77], v[246:249], v[50:53]
	s_nop 0
	ds_read_b128 v[246:249], v178 offset:52352
	s_nop 0
	s_waitcnt lgkmcnt(4)
	v_mfma_f32_16x16x32_bf16 v[50:53], v[70:73], v[250:253], v[50:53]
	s_nop 0
	ds_read_b128 v[250:253], v178 offset:52416
	s_nop 0
	s_waitcnt lgkmcnt(4)
	v_mfma_f32_16x16x32_bf16 v[50:53], v[66:69], v[234:237], v[50:53]
	s_nop 0
	ds_read_b128 v[234:237], v178 offset:56576
	s_nop 0
	s_waitcnt lgkmcnt(4)
	v_mfma_f32_16x16x32_bf16 v[42:45], v[78:81], v[238:241], v[42:45]
	s_nop 0
	ds_read_b128 v[238:241], v178 offset:56640
	s_nop 0
	s_waitcnt lgkmcnt(4)
	v_mfma_f32_16x16x32_bf16 v[42:45], v[74:77], v[242:245], v[42:45]
	s_nop 0
	ds_read_b128 v[242:245], v178 offset:56704
	s_nop 0
	s_waitcnt lgkmcnt(4)
	v_mfma_f32_16x16x32_bf16 v[42:45], v[70:73], v[246:249], v[42:45]
	s_nop 0
	ds_read_b128 v[246:249], v178 offset:56768
	s_nop 0
	s_waitcnt lgkmcnt(4)
	v_mfma_f32_16x16x32_bf16 v[42:45], v[66:69], v[250:253], v[42:45]
	s_nop 0
	ds_read_b128 v[250:253], v178 offset:60928
	s_nop 0
	s_waitcnt lgkmcnt(4)
	v_mfma_f32_16x16x32_bf16 v[38:41], v[78:81], v[234:237], v[38:41]
	s_nop 0
	ds_read_b128 v[234:237], v178 offset:60992
	s_nop 0
	s_waitcnt lgkmcnt(4)
	v_mfma_f32_16x16x32_bf16 v[38:41], v[74:77], v[238:241], v[38:41]
	s_nop 0
	ds_read_b128 v[238:241], v178 offset:61056
	s_nop 0
	s_waitcnt lgkmcnt(4)
	v_mfma_f32_16x16x32_bf16 v[38:41], v[70:73], v[242:245], v[38:41]
	s_nop 0
	ds_read_b128 v[242:245], v178 offset:61120
	s_nop 0
	s_waitcnt lgkmcnt(4)
	v_mfma_f32_16x16x32_bf16 v[38:41], v[66:69], v[246:249], v[38:41]
	s_nop 0
	s_nop 0
	s_waitcnt lgkmcnt(3)
	v_mfma_f32_16x16x32_bf16 v[34:37], v[78:81], v[250:253], v[34:37]
	s_nop 0
	s_nop 0
	s_waitcnt lgkmcnt(2)
	v_mfma_f32_16x16x32_bf16 v[34:37], v[74:77], v[234:237], v[34:37]
	s_nop 0
	s_nop 0
	s_waitcnt lgkmcnt(1)
	v_mfma_f32_16x16x32_bf16 v[34:37], v[70:73], v[238:241], v[34:37]
	s_nop 0
	s_nop 0
	s_waitcnt lgkmcnt(0)
	v_mfma_f32_16x16x32_bf16 v[34:37], v[66:69], v[242:245], v[34:37]
	ds_read_b128 v[84:87], v178 offset:65280
	s_nop 0
	s_waitcnt lgkmcnt(0)
	v_mfma_f32_16x16x32_bf16 v[54:57], v[78:81], v[84:87], v[54:57]
	ds_read_b128 v[78:81], v178 offset:65344
	s_nop 0
	s_waitcnt lgkmcnt(0)
	v_mfma_f32_16x16x32_bf16 v[54:57], v[74:77], v[78:81], v[54:57]
	ds_read_b128 v[74:77], v178 offset:65408
	s_nop 0
	s_waitcnt lgkmcnt(0)
	v_mfma_f32_16x16x32_bf16 v[54:57], v[70:73], v[74:77], v[54:57]
	ds_read_b128 v[70:73], v178 offset:65472
	s_nop 0
	s_waitcnt lgkmcnt(0)
	v_mfma_f32_16x16x32_bf16 v[54:57], v[66:69], v[70:73], v[54:57]
	v_lshrrev_b32_e32 v66, 6, v163
	v_and_b32_e32 v67, 15, v163
	v_lshl_add_u32 v66, v66, 4, v67
	v_bfe_u32 v67, v163, 4, 2
	v_mul_u32_u24_e32 v68, 0x110, v66
	v_lshl_add_u32 v67, v67, 4, v68
	v_lshlrev_b32_e32 v66, 2, v66
	v_add_u32_e32 v66, 0x22600, v66
	v_mov_b32_e32 v76, 0x3f803f80
	v_mov_b32_e32 v77, 0x3f803f80
	v_mov_b32_e32 v78, 0x3f803f80
	v_mov_b32_e32 v79, 0x3f803f80
	ds_read_b128 v[68:71], v67 offset:34816
	ds_read_b128 v[72:75], v67 offset:34880
	s_waitcnt lgkmcnt(1)
	v_mfma_f32_16x16x32_bf16 v[84:87], v[76:79], v[68:71], 0
	ds_read_b128 v[68:71], v67 offset:34944
	s_waitcnt lgkmcnt(1)
	v_mfma_f32_16x16x32_bf16 v[84:87], v[76:79], v[72:75], v[84:87]
	ds_read_b128 v[72:75], v67 offset:35008
	ds_read_b32 v67, v66
	s_waitcnt lgkmcnt(2)
	v_mfma_f32_16x16x32_bf16 v[84:87], v[76:79], v[68:71], v[84:87]
	s_waitcnt lgkmcnt(1)
	v_mfma_f32_16x16x32_bf16 v[84:87], v[76:79], v[72:75], v[84:87]
	s_waitcnt lgkmcnt(0)
	s_nop 7
	s_nop 1
	v_fmac_f32_e32 v84, v82, v67

.LBB0_691:
	ds_read_b32 v155, v125
	s_waitcnt vmcnt(3)
	v_and_b32_e32 v187, 0xffff0000, v78
	v_lshlrev_b32_e32 v186, 16, v78
	s_waitcnt vmcnt(2)
	v_and_b32_e32 v191, 0xffff0000, v74
	v_and_b32_e32 v190, 0xffff0000, v80
	s_waitcnt lgkmcnt(0)
	v_sub_f32_e32 v82, v154, v155
	v_mul_f32_e32 v156, 0x3fb8aa3b, v82
	ds_read_b128 v[82:85], v138
	ds_read_b128 v[86:89], v138 offset:1088
	ds_read_b128 v[90:93], v138 offset:64
	ds_read_b128 v[94:97], v138 offset:1152
	v_lshlrev_b64 v[110:111], 10, v[110:111]
	s_waitcnt lgkmcnt(3)
	v_mfma_f32_16x16x32_bf16 v[82:85], v[82:85], v[78:81], 0
	s_mov_b32 s90, 0
	s_waitcnt lgkmcnt(2)
	v_mfma_f32_16x16x32_bf16 v[86:89], v[86:89], v[78:81], 0
	s_waitcnt lgkmcnt(1)
	v_mfma_f32_16x16x32_bf16 v[82:85], v[90:93], v[74:77], v[82:85]
	s_waitcnt lgkmcnt(0)
	v_mfma_f32_16x16x32_bf16 v[86:89], v[94:97], v[74:77], v[86:89]
	ds_read_b128 v[90:93], v138 offset:128
	ds_read_b128 v[94:97], v138 offset:1216
	s_waitcnt vmcnt(1) lgkmcnt(1)
	v_mfma_f32_16x16x32_bf16 v[82:85], v[90:93], v[70:73], v[82:85]
	s_waitcnt lgkmcnt(0)
	v_mfma_f32_16x16x32_bf16 v[86:89], v[94:97], v[70:73], v[86:89]
	ds_read_b128 v[90:93], v138 offset:192
	ds_read_b128 v[94:97], v138 offset:1280
	s_waitcnt vmcnt(0) lgkmcnt(1)
	v_mfma_f32_16x16x32_bf16 v[82:85], v[90:93], v[66:69], v[82:85]
	s_cmp_gt_u32 s1, 14
	s_cbranch_scc1 .Lml_pf_skip1
	s_lshl_b32 s1, s2, 7
	v_add_u32_e32 v34, s1, v114
	v_add_u32_e32 v36, s1, v116
	v_add_u32_e32 v42, s1, v117
	v_add_u32_e32 v44, s1, v118
	v_sub_u32_e32 v35, 0x7ff, v34
	v_sub_u32_e32 v37, 0x7ff, v36
	v_sub_u32_e32 v43, 0x7ff, v42
	v_sub_u32_e32 v45, 0x7ff, v44
	v_cndmask_b32_e64 v34, v35, v34, s[6:7]
	v_cndmask_b32_e64 v36, v37, v36, s[6:7]
	v_cndmask_b32_e64 v42, v43, v42, s[6:7]
	v_cndmask_b32_e64 v44, v45, v44, s[6:7]
	v_add_u32_e32 v34, s0, v34
	v_add_u32_e32 v36, s0, v36
	v_add_u32_e32 v42, s0, v42
	v_add_u32_e32 v44, s0, v44
	v_ashrrev_i32_e32 v35, 31, v34
	v_ashrrev_i32_e32 v37, 31, v36
	v_ashrrev_i32_e32 v43, 31, v42
	v_ashrrev_i32_e32 v45, 31, v44
	v_lshlrev_b64 v[34:35], 11, v[34:35]
	v_lshlrev_b64 v[36:37], 11, v[36:37]
	v_lshlrev_b64 v[42:43], 11, v[42:43]
	v_lshlrev_b64 v[44:45], 11, v[44:45]
	v_lshl_add_u64 v[34:35], v[108:109], 0, v[34:35]
	v_lshl_add_u64 v[38:39], v[108:109], 0, v[36:37]
	v_lshl_add_u64 v[42:43], v[108:109], 0, v[42:43]
	v_lshl_add_u64 v[46:47], v[108:109], 0, v[44:45]
	global_load_dwordx4 v[34:37], v[34:35], off offset:1024
	s_nop 0
	global_load_dwordx4 v[38:41], v[38:39], off offset:1024
	s_nop 0
	global_load_dwordx4 v[42:45], v[42:43], off offset:1024
	s_nop 0
	global_load_dwordx4 v[46:49], v[46:47], off offset:1024
	s_and_saveexec_b64 s[90:91], s[8:9]
	s_cbranch_execz .LBB0_688
	v_or_b32_e32 v60, s1, v120
	v_sub_u32_e32 v50, 0x7ff, v60
	v_cndmask_b32_e64 v50, v50, v60, s[6:7]
	v_or_b32_e32 v52, 1, v60
	v_xad_u32 v53, v60, -2, v216
	v_or_b32_e32 v58, 2, v60
	v_xad_u32 v59, v60, -3, v216
	v_or_b32_e32 v61, 3, v60
	v_xad_u32 v60, v60, -4, v216
	v_cndmask_b32_e64 v52, v53, v52, s[6:7]
	v_cndmask_b32_e64 v58, v59, v58, s[6:7]
	v_cndmask_b32_e64 v60, v60, v61, s[6:7]
	v_add_u32_e32 v50, s0, v50
	v_add_u32_e32 v52, s0, v52
	v_add_u32_e32 v58, s0, v58
	v_add_u32_e32 v60, s0, v60
	v_ashrrev_i32_e32 v51, 31, v50
	v_ashrrev_i32_e32 v53, 31, v52
	v_ashrrev_i32_e32 v59, 31, v58
	v_ashrrev_i32_e32 v61, 31, v60
	v_lshlrev_b64 v[50:51], 11, v[50:51]
	v_lshlrev_b64 v[52:53], 11, v[52:53]
	v_lshlrev_b64 v[58:59], 11, v[58:59]
	v_lshlrev_b64 v[60:61], 11, v[60:61]
	v_lshl_add_u64 v[50:51], v[106:107], 0, v[50:51]
	v_lshl_add_u64 v[54:55], v[106:107], 0, v[52:53]
	v_lshl_add_u64 v[58:59], v[106:107], 0, v[58:59]
	v_lshl_add_u64 v[62:63], v[106:107], 0, v[60:61]
	global_load_dwordx4 v[50:53], v[50:51], off
	s_nop 0
	global_load_dwordx4 v[54:57], v[54:55], off
	s_nop 0
	global_load_dwordx4 v[58:61], v[58:59], off
	s_nop 0
	global_load_dwordx4 v[62:65], v[62:63], off
.LBB0_688:
	s_or_b64 exec, exec, s[90:91]
	s_and_saveexec_b64 s[90:91], s[10:11]
	s_cbranch_execz .LBB0_690
	v_or_b32_e32 v236, s1, v121
	v_sub_u32_e32 v234, 0x7ff, v236
	v_cndmask_b32_e64 v234, v234, v236, s[6:7]
	v_or_b32_e32 v237, 1, v236
	v_xad_u32 v236, v236, -2, v216
	v_add_u32_e32 v234, s0, v234
	v_cndmask_b32_e64 v236, v236, v237, s[6:7]
	v_ashrrev_i32_e32 v235, 31, v234
	v_readlane_b32 s96, v254, 62
	v_add_u32_e32 v236, s0, v236
	v_lshlrev_b64 v[234:235], 6, v[234:235]
	v_readlane_b32 s97, v254, 63
	v_ashrrev_i32_e32 v237, 31, v236
	v_lshlrev_b64 v[236:237], 6, v[236:237]
	v_lshl_add_u64 v[234:235], s[96:97], 0, v[234:235]
	v_lshl_add_u64 v[236:237], s[96:97], 0, v[236:237]
	global_load_dword v102, v[234:235], off
	global_load_dword v123, v[234:235], off offset:16
	global_load_dword v103, v[236:237], off
	global_load_dword v124, v[236:237], off offset:16

.Lml_pf_skip1:
	s_waitcnt lgkmcnt(0)
	v_mfma_f32_16x16x32_bf16 v[86:89], v[94:97], v[66:69], v[86:89]
	ds_read_b128 v[90:93], v127
	ds_read_b128 v[94:97], v127 offset:16
	s_waitcnt lgkmcnt(1)
	v_sub_f32_e32 v90, v90, v155
	v_sub_f32_e32 v91, v91, v155
	v_mul_f32_e32 v90, 0x3fb8aa3b, v90
	v_mul_f32_e32 v91, 0x3fb8aa3b, v91
	v_exp_f32_e32 v90, v90
	v_exp_f32_e32 v91, v91
	v_mul_f32_e32 v82, v82, v90
	v_mul_f32_e32 v83, v83, v91
	v_cndmask_b32_e64 v90, v82, 0, s[24:25]
	s_waitcnt lgkmcnt(0)
	v_sub_f32_e32 v82, v94, v155
	v_cndmask_b32_e64 v91, 0, v83, s[26:27]
	v_sub_f32_e32 v83, v95, v155
	v_mul_f32_e32 v82, 0x3fb8aa3b, v82
	v_mul_f32_e32 v83, 0x3fb8aa3b, v83
	v_exp_f32_e32 v82, v82
	v_exp_f32_e32 v83, v83
	s_nop 0
	v_pk_mul_f32 v[82:83], v[86:87], v[82:83]
	s_nop 0
	v_cndmask_b32_e64 v95, v83, 0, s[28:29]
	v_sub_f32_e32 v83, v96, v155
	v_mul_f32_e32 v83, 0x3fb8aa3b, v83
	v_cndmask_b32_e64 v98, v82, 0, s[30:31]
	v_sub_f32_e32 v82, v92, v155
	v_exp_f32_e32 v86, v83
	v_sub_f32_e32 v83, v93, v155
	v_mul_f32_e32 v82, 0x3fb8aa3b, v82
	v_mul_f32_e32 v83, 0x3fb8aa3b, v83
	v_exp_f32_e32 v82, v82
	v_exp_f32_e32 v83, v83
	s_nop 0
	v_pk_mul_f32 v[82:83], v[84:85], v[82:83]
	s_nop 0
	v_cndmask_b32_e64 v85, v82, 0, s[36:37]
	v_sub_f32_e32 v82, v97, v155
	v_mul_f32_e32 v82, 0x3fb8aa3b, v82
	v_exp_f32_e32 v87, v82
	v_cndmask_b32_e64 v84, v83, 0, s[34:35]
	v_pk_mul_f32 v[82:83], v[88:89], v[86:87]
	s_nop 0
	v_cndmask_b32_e64 v87, v82, 0, s[40:41]
	v_add_f32_e32 v82, 0, v90
	v_add_f32_e32 v82, v91, v82
	v_add_f32_e32 v82, v85, v82
	v_add_f32_e32 v82, v84, v82
	v_add_f32_e32 v82, v98, v82
	v_add_f32_e32 v82, v95, v82
	v_cndmask_b32_e64 v86, v83, 0, s[38:39]
	v_add_f32_e32 v82, v87, v82
	v_add_f32_e32 v94, v86, v82
	v_cvt_pk_bf16_f32 v82, v90, v91
	v_cvt_pk_bf16_f32 v83, v85, v84
	v_cvt_pk_bf16_f32 v85, v87, v86
	ds_read_b128 v[86:89], v138 offset:8704
	ds_read_b128 v[90:93], v138 offset:9792
	v_cvt_pk_bf16_f32 v84, v98, v95
	ds_read_b128 v[96:99], v138 offset:8768
	ds_read_b128 v[158:161], v138 offset:9856
	s_waitcnt lgkmcnt(3)
	v_mfma_f32_16x16x32_bf16 v[86:89], v[86:89], v[78:81], 0
	s_waitcnt lgkmcnt(2)
	v_mfma_f32_16x16x32_bf16 v[90:93], v[90:93], v[78:81], 0
	s_waitcnt lgkmcnt(1)
	v_mfma_f32_16x16x32_bf16 v[86:89], v[96:99], v[74:77], v[86:89]
	s_waitcnt lgkmcnt(0)
	v_mfma_f32_16x16x32_bf16 v[90:93], v[158:161], v[74:77], v[90:93]
	ds_read_b128 v[96:99], v138 offset:8832
	ds_read_b128 v[158:161], v138 offset:9920
	s_waitcnt lgkmcnt(1)
	v_mfma_f32_16x16x32_bf16 v[86:89], v[96:99], v[70:73], v[86:89]
	s_waitcnt lgkmcnt(0)
	v_mfma_f32_16x16x32_bf16 v[96:99], v[158:161], v[70:73], v[90:93]
	s_nop 2
	ds_read_b128 v[90:93], v138 offset:8896
	ds_read_b128 v[158:161], v138 offset:9984
	s_waitcnt lgkmcnt(1)
	v_mfma_f32_16x16x32_bf16 v[90:93], v[90:93], v[66:69], v[86:89]
	s_waitcnt lgkmcnt(0)
	v_mfma_f32_16x16x32_bf16 v[86:89], v[158:161], v[66:69], v[96:99]
	s_nop 2
	ds_read_b128 v[96:99], v127 offset:128
	ds_read_b128 v[158:161], v127 offset:144
	s_waitcnt lgkmcnt(1)
	v_sub_f32_e32 v95, v96, v155
	v_mul_f32_e32 v95, 0x3fb8aa3b, v95
	v_exp_f32_e32 v96, v95
	s_waitcnt lgkmcnt(0)
	v_sub_f32_e32 v95, v158, v155
	v_mul_f32_e32 v95, 0x3fb8aa3b, v95
	v_exp_f32_e32 v100, v95
	v_sub_f32_e32 v95, v97, v155
	v_mul_f32_e32 v95, 0x3fb8aa3b, v95
	v_exp_f32_e32 v97, v95
	s_nop 0
	v_pk_mul_f32 v[90:91], v[90:91], v[96:97]
	s_nop 0
	v_cndmask_b32_e64 v96, v90, 0, s[44:45]
	v_sub_f32_e32 v90, v159, v155
	v_mul_f32_e32 v90, 0x3fb8aa3b, v90
	v_exp_f32_e32 v101, v90
	v_cndmask_b32_e64 v95, v91, 0, s[42:43]
	v_pk_mul_f32 v[86:87], v[86:87], v[100:101]
	s_nop 0
	v_cndmask_b32_e64 v97, v87, 0, s[46:47]
	v_sub_f32_e32 v87, v160, v155
	v_mul_f32_e32 v87, 0x3fb8aa3b, v87
	v_cndmask_b32_e64 v100, v86, 0, s[48:49]
	v_sub_f32_e32 v86, v98, v155
	v_exp_f32_e32 v90, v87
	v_sub_f32_e32 v87, v99, v155
	v_mul_f32_e32 v86, 0x3fb8aa3b, v86
	v_mul_f32_e32 v87, 0x3fb8aa3b, v87
	v_exp_f32_e32 v86, v86
	v_exp_f32_e32 v87, v87
	s_nop 0
	v_pk_mul_f32 v[86:87], v[92:93], v[86:87]
	s_nop 0
	v_cndmask_b32_e64 v93, v86, 0, s[52:53]
	v_sub_f32_e32 v86, v161, v155
	v_mul_f32_e32 v86, 0x3fb8aa3b, v86
	v_exp_f32_e32 v91, v86
	v_cndmask_b32_e64 v92, v87, 0, s[50:51]
	v_pk_mul_f32 v[86:87], v[88:89], v[90:91]
	s_nop 0
	v_cndmask_b32_e64 v90, v86, 0, s[56:57]
	v_add_f32_e32 v86, v94, v96
	v_add_f32_e32 v86, v95, v86
	v_add_f32_e32 v86, v93, v86
	v_add_f32_e32 v86, v92, v86
	v_add_f32_e32 v86, v100, v86
	v_add_f32_e32 v86, v97, v86
	v_cndmask_b32_e64 v89, v87, 0, s[54:55]
	v_add_f32_e32 v86, v90, v86
	v_add_f32_e32 v98, v89, v86
	v_cvt_pk_bf16_f32 v86, v96, v95
	v_cvt_pk_bf16_f32 v87, v93, v92
	v_cvt_pk_bf16_f32 v88, v100, v97
	v_cvt_pk_bf16_f32 v89, v90, v89
	ds_read_b128 v[90:93], v138 offset:17408
	ds_read_b128 v[94:97], v138 offset:18496
	ds_read_b128 v[158:161], v138 offset:17472
	ds_read_b128 v[176:179], v138 offset:18560
	s_waitcnt lgkmcnt(3)
	v_mfma_f32_16x16x32_bf16 v[90:93], v[90:93], v[78:81], 0
	s_waitcnt lgkmcnt(2)
	v_mfma_f32_16x16x32_bf16 v[94:97], v[94:97], v[78:81], 0
	s_waitcnt lgkmcnt(1)
	v_mfma_f32_16x16x32_bf16 v[90:93], v[158:161], v[74:77], v[90:93]
	s_waitcnt lgkmcnt(0)
	v_mfma_f32_16x16x32_bf16 v[94:97], v[176:179], v[74:77], v[94:97]
	ds_read_b128 v[158:161], v138 offset:17536
	ds_read_b128 v[176:179], v138 offset:18624
	s_waitcnt lgkmcnt(1)
	v_mfma_f32_16x16x32_bf16 v[90:93], v[158:161], v[70:73], v[90:93]
	s_waitcnt lgkmcnt(0)
	v_mfma_f32_16x16x32_bf16 v[158:161], v[176:179], v[70:73], v[94:97]
	s_nop 2
	ds_read_b128 v[94:97], v138 offset:17600
	ds_read_b128 v[176:179], v138 offset:18688
	s_waitcnt lgkmcnt(1)
	v_mfma_f32_16x16x32_bf16 v[94:97], v[94:97], v[66:69], v[90:93]
	s_waitcnt lgkmcnt(0)
	v_mfma_f32_16x16x32_bf16 v[90:93], v[176:179], v[66:69], v[158:161]
	s_nop 2
	ds_read_b128 v[158:161], v127 offset:256
	ds_read_b128 v[176:179], v127 offset:272
	s_waitcnt lgkmcnt(1)
	v_sub_f32_e32 v99, v158, v155
	v_mul_f32_e32 v99, 0x3fb8aa3b, v99
	v_exp_f32_e32 v100, v99
	s_waitcnt lgkmcnt(0)
	v_sub_f32_e32 v99, v176, v155
	v_mul_f32_e32 v99, 0x3fb8aa3b, v99
	v_exp_f32_e32 v158, v99
	v_sub_f32_e32 v99, v159, v155
	v_mul_f32_e32 v99, 0x3fb8aa3b, v99
	v_exp_f32_e32 v101, v99
	s_nop 0
	v_pk_mul_f32 v[94:95], v[94:95], v[100:101]
	s_nop 0
	v_cndmask_b32_e64 v100, v94, 0, s[60:61]
	v_sub_f32_e32 v94, v177, v155
	v_mul_f32_e32 v94, 0x3fb8aa3b, v94
	v_exp_f32_e32 v159, v94
	v_cndmask_b32_e64 v99, v95, 0, s[58:59]
	v_pk_mul_f32 v[90:91], v[90:91], v[158:159]
	s_nop 0
	v_cndmask_b32_e64 v101, v91, 0, s[62:63]
	v_sub_f32_e32 v91, v178, v155
	v_mul_f32_e32 v91, 0x3fb8aa3b, v91
	v_cndmask_b32_e64 v158, v90, 0, s[64:65]
	v_sub_f32_e32 v90, v160, v155
	v_exp_f32_e32 v94, v91
	v_sub_f32_e32 v91, v161, v155
	v_mul_f32_e32 v90, 0x3fb8aa3b, v90
	v_mul_f32_e32 v91, 0x3fb8aa3b, v91
	v_exp_f32_e32 v90, v90
	v_exp_f32_e32 v91, v91
	s_nop 0
	v_pk_mul_f32 v[90:91], v[96:97], v[90:91]
	s_nop 0
	v_cndmask_b32_e64 v97, v90, 0, s[68:69]
	v_sub_f32_e32 v90, v179, v155
	v_mul_f32_e32 v90, 0x3fb8aa3b, v90
	v_exp_f32_e32 v95, v90
	v_cndmask_b32_e64 v96, v91, 0, s[66:67]
	v_pk_mul_f32 v[90:91], v[92:93], v[94:95]
	s_nop 0
	v_cndmask_b32_e64 v94, v90, 0, s[72:73]
	v_add_f32_e32 v90, v98, v100
	v_add_f32_e32 v90, v99, v90
	v_add_f32_e32 v90, v97, v90
	v_add_f32_e32 v90, v96, v90
	v_add_f32_e32 v90, v158, v90
	v_add_f32_e32 v90, v101, v90
	v_cndmask_b32_e64 v93, v91, 0, s[70:71]
	v_add_f32_e32 v90, v94, v90
	v_add_f32_e32 v157, v93, v90
	v_cvt_pk_bf16_f32 v90, v100, v99
	v_cvt_pk_bf16_f32 v91, v97, v96
	v_cvt_pk_bf16_f32 v92, v158, v101
	v_cvt_pk_bf16_f32 v93, v94, v93
	ds_read_b128 v[94:97], v138 offset:26112
	ds_read_b128 v[98:101], v138 offset:27200
	ds_read_b128 v[158:161], v138 offset:26176
	ds_read_b128 v[176:179], v138 offset:27264
	s_waitcnt lgkmcnt(3)
	v_mfma_f32_16x16x32_bf16 v[94:97], v[94:97], v[78:81], 0
	s_waitcnt lgkmcnt(2)
	v_mfma_f32_16x16x32_bf16 v[98:101], v[98:101], v[78:81], 0
	s_waitcnt lgkmcnt(1)
	v_mfma_f32_16x16x32_bf16 v[94:97], v[158:161], v[74:77], v[94:97]
	s_waitcnt lgkmcnt(0)
	v_mfma_f32_16x16x32_bf16 v[98:101], v[176:179], v[74:77], v[98:101]
	ds_read_b128 v[158:161], v138 offset:26240
	ds_read_b128 v[176:179], v138 offset:27328
	s_waitcnt lgkmcnt(1)
	v_mfma_f32_16x16x32_bf16 v[94:97], v[158:161], v[70:73], v[94:97]
	s_waitcnt lgkmcnt(0)
	v_mfma_f32_16x16x32_bf16 v[158:161], v[176:179], v[70:73], v[98:101]
	s_nop 2
	ds_read_b128 v[98:101], v138 offset:26304
	ds_read_b128 v[176:179], v138 offset:27392
	s_waitcnt lgkmcnt(1)
	v_mfma_f32_16x16x32_bf16 v[98:101], v[98:101], v[66:69], v[94:97]
	s_waitcnt lgkmcnt(0)
	v_mfma_f32_16x16x32_bf16 v[94:97], v[176:179], v[66:69], v[158:161]
	s_nop 2
	ds_read_b128 v[158:161], v127 offset:384
	ds_read_b128 v[176:179], v127 offset:400
	s_waitcnt lgkmcnt(1)
	v_sub_f32_e32 v158, v158, v155
	v_sub_f32_e32 v159, v159, v155
	v_mul_f32_e32 v158, 0x3fb8aa3b, v158
	v_mul_f32_e32 v159, 0x3fb8aa3b, v159
	v_exp_f32_e32 v158, v158
	v_exp_f32_e32 v159, v159
	s_waitcnt lgkmcnt(0)
	v_sub_f32_e32 v169, v176, v155
	v_mul_f32_e32 v169, 0x3fb8aa3b, v169
	v_exp_f32_e32 v176, v169
	v_pk_mul_f32 v[98:99], v[98:99], v[158:159]
	s_nop 0
	v_cndmask_b32_e64 v159, v98, 0, s[76:77]
	v_sub_f32_e32 v98, v177, v155
	v_mul_f32_e32 v98, 0x3fb8aa3b, v98
	v_exp_f32_e32 v177, v98
	v_cndmask_b32_e64 v158, v99, 0, s[74:75]
	v_pk_mul_f32 v[94:95], v[94:95], v[176:177]
	s_nop 0
	v_cndmask_b32_e64 v176, v95, 0, s[78:79]
	v_sub_f32_e32 v95, v178, v155
	v_mul_f32_e32 v95, 0x3fb8aa3b, v95
	v_cndmask_b32_e64 v180, v94, 0, s[80:81]
	v_sub_f32_e32 v94, v160, v155
	v_exp_f32_e32 v98, v95
	v_sub_f32_e32 v95, v161, v155
	v_mul_f32_e32 v94, 0x3fb8aa3b, v94
	v_mul_f32_e32 v95, 0x3fb8aa3b, v95
	v_exp_f32_e32 v94, v94
	v_exp_f32_e32 v95, v95
	s_nop 0
	v_pk_mul_f32 v[94:95], v[100:101], v[94:95]
	s_nop 0
	v_cndmask_b32_e64 v101, v94, 0, s[84:85]
	v_sub_f32_e32 v94, v179, v155
	v_mul_f32_e32 v94, 0x3fb8aa3b, v94
	v_exp_f32_e32 v99, v94
	v_cndmask_b32_e64 v100, v95, 0, s[82:83]
	v_pk_mul_f32 v[94:95], v[96:97], v[98:99]
	s_nop 0
	v_cndmask_b32_e64 v182, v94, 0, s[88:89]
	v_add_f32_e32 v94, v157, v159
	v_add_f32_e32 v94, v158, v94
	v_add_u32_e32 v98, 0, v126
	v_add_f32_e32 v94, v101, v94
	v_add_u32_e32 v157, 0x22600, v98
	v_cndmask_b32_e64 v178, v95, 0, s[86:87]
	v_add_f32_e32 v184, v100, v94
	v_cvt_pk_bf16_f32 v94, v159, v158
	v_cvt_pk_bf16_f32 v95, v101, v100
	ds_read_b128 v[98:101], v157
	ds_read_b128 v[158:161], v157 offset:16
	v_cvt_pk_bf16_f32 v96, v180, v176
	v_cvt_pk_bf16_f32 v97, v182, v178
	s_waitcnt lgkmcnt(1)
	v_pk_mul_f32 v[98:99], v[98:99], v[186:187]
	v_and_b32_e32 v187, 0xffff0000, v79
	v_lshlrev_b32_e32 v186, 16, v79
	v_pk_mul_f32 v[100:101], v[100:101], v[186:187]
	v_add_f32_e32 v98, v98, v99
	v_add_f32_e32 v98, v100, v98
	v_add_f32_e32 v98, v101, v98
	v_add_f32_e32 v169, 0, v98
	ds_read_b128 v[98:101], v157 offset:128
	v_lshlrev_b32_e32 v187, 16, v74
	v_lshlrev_b32_e32 v186, 16, v80
	s_waitcnt lgkmcnt(1)
	v_mov_b32_e32 v188, v158
	v_lshlrev_b32_e32 v158, 16, v81
	s_waitcnt lgkmcnt(0)
	v_mov_b32_e32 v189, v98
	v_mov_b32_e32 v98, v159
	v_pk_mul_f32 v[98:99], v[98:99], v[190:191]
	v_lshlrev_b32_e32 v159, 16, v75
	v_pk_fma_f32 v[98:99], v[188:189], v[186:187], v[98:99]
	v_mov_b32_e32 v186, v160
	v_mov_b32_e32 v187, v100
	v_pk_fma_f32 v[98:99], v[186:187], v[158:159], v[98:99]
	v_and_b32_e32 v159, 0xffff0000, v75
	v_and_b32_e32 v158, 0xffff0000, v81
	v_mov_b32_e32 v100, v161
	v_pk_fma_f32 v[98:99], v[100:101], v[158:159], v[98:99]
	v_and_b32_e32 v191, 0xffff0000, v70
	v_add_f32_e32 v98, v169, v98
	v_add_f32_e32 v169, v98, v99
	ds_read_b128 v[98:101], v157 offset:144
	ds_read_b128 v[158:161], v157 offset:256
	v_and_b32_e32 v190, 0xffff0000, v76
	v_lshlrev_b32_e32 v187, 16, v70
	v_lshlrev_b32_e32 v186, 16, v76
	s_waitcnt lgkmcnt(1)
	v_mov_b32_e32 v188, v98
	s_waitcnt lgkmcnt(0)
	v_mov_b32_e32 v189, v158
	v_mov_b32_e32 v158, v99
	v_pk_mul_f32 v[98:99], v[158:159], v[190:191]
	v_lshlrev_b32_e32 v159, 16, v71
	v_pk_fma_f32 v[98:99], v[188:189], v[186:187], v[98:99]
	v_lshlrev_b32_e32 v158, 16, v77
	v_mov_b32_e32 v186, v100
	v_mov_b32_e32 v187, v160
	v_pk_fma_f32 v[98:99], v[186:187], v[158:159], v[98:99]
	v_and_b32_e32 v159, 0xffff0000, v71
	v_and_b32_e32 v158, 0xffff0000, v77
	v_mov_b32_e32 v160, v101
	v_pk_fma_f32 v[98:99], v[160:161], v[158:159], v[98:99]
	v_and_b32_e32 v191, 0xffff0000, v66
	v_add_f32_e32 v98, v169, v98
	v_add_f32_e32 v169, v98, v99
	ds_read_b128 v[98:101], v157 offset:272
	ds_read_b128 v[158:161], v157 offset:384
	v_and_b32_e32 v190, 0xffff0000, v72
	v_lshlrev_b32_e32 v187, 16, v66
	v_lshlrev_b32_e32 v186, 16, v72
	s_waitcnt lgkmcnt(1)
	v_mov_b32_e32 v188, v98
	s_waitcnt lgkmcnt(0)
	v_mov_b32_e32 v189, v158
	v_mov_b32_e32 v158, v99
	v_pk_mul_f32 v[98:99], v[158:159], v[190:191]
	v_lshlrev_b32_e32 v159, 16, v67
	v_pk_fma_f32 v[98:99], v[188:189], v[186:187], v[98:99]
	v_lshlrev_b32_e32 v158, 16, v73
	v_mov_b32_e32 v186, v100
	v_mov_b32_e32 v187, v160
	v_pk_fma_f32 v[98:99], v[186:187], v[158:159], v[98:99]
	v_and_b32_e32 v159, 0xffff0000, v67
	v_and_b32_e32 v158, 0xffff0000, v73
	v_mov_b32_e32 v160, v101
	v_pk_fma_f32 v[98:99], v[160:161], v[158:159], v[98:99]
	s_nop 0
	v_add_f32_e32 v98, v169, v98
	v_add_f32_e32 v179, v98, v99
	ds_read_b128 v[98:101], v157 offset:400
	v_lshlrev_b32_e32 v157, 16, v68
	s_waitcnt lgkmcnt(0)
	v_mul_f32_e32 v181, v98, v157
	v_and_b32_e32 v98, 0xffff0000, v68
	v_mul_f32_e32 v185, v99, v98
	v_lshlrev_b32_e32 v98, 16, v69
	v_mul_f32_e32 v177, v100, v98
	v_and_b32_e32 v98, 0xffff0000, v69
	v_mul_f32_e32 v183, v101, v98
	v_pk_add_f32 v[100:101], v[180:181], v[184:185]
	v_exp_f32_e32 v98, v156
	v_pk_add_f32 v[100:101], v[176:177], v[100:101]
	ds_read_b32 v99, v130
	v_pk_add_f32 v[100:101], v[182:183], v[100:101]
	s_nop 0
	v_pk_add_f32 v[100:101], v[178:179], v[100:101]
	ds_bpermute_b32 v156, v128, v100
	ds_bpermute_b32 v157, v128, v101
	ds_read_b128 v[176:179], v148 offset:64
	s_waitcnt lgkmcnt(3)
	v_add_f32_e32 v99, v155, v99
	v_mul_f32_e32 v99, 0xbfb8aa3b, v99
	v_exp_f32_e32 v99, v99
	s_waitcnt lgkmcnt(1)
	v_pk_add_f32 v[100:101], v[100:101], v[156:157]
	ds_bpermute_b32 v156, v129, v100
	ds_bpermute_b32 v157, v129, v101
	s_waitcnt lgkmcnt(0)
	v_pk_add_f32 v[100:101], v[100:101], v[156:157]
	s_nop 0
	v_fmac_f32_e32 v100, v98, v101
	v_max_f32_e64 v99, |v100|, v99
	v_div_scale_f32 v100, s[96:97], v99, v99, 1.0
	v_rcp_f32_e32 v101, v100
	v_readlane_b32 s96, v254, 25
	v_readlane_b32 s97, v254, 26
	s_load_dwordx2 s[96:97], s[96:97], 0x118
	v_fma_f32 v155, -v100, v101, 1.0
	v_fmac_f32_e32 v101, v155, v101
	v_div_scale_f32 v155, vcc, 1.0, v99, 1.0
	v_mul_f32_e32 v156, v155, v101
	v_fma_f32 v157, -v100, v156, v155
	v_fmac_f32_e32 v156, v157, v101
	v_fma_f32 v100, -v100, v156, v155
	v_div_fmas_f32 v100, v100, v101, v156
	s_waitcnt lgkmcnt(0)
	ds_read_b128 v[234:237], v148
	ds_read_b128 v[238:241], v148 offset:128
	ds_read_b128 v[242:245], v148 offset:192
	ds_read_b128 v[246:249], v149
	ds_read_b128 v[250:253], v149 offset:64
	s_nop 0
	s_waitcnt lgkmcnt(4)
	v_mfma_f32_16x16x32_bf16 v[156:159], v[234:237], v[78:81], 0
	ds_read_b128 v[234:237], v149 offset:128
	v_lshl_add_u64 v[112:113], s[96:97], 0, v[112:113]
	s_mov_b64 s[96:97], 0x2134200
	v_lshl_add_u64 v[112:113], v[112:113], 0, s[96:97]
	v_mfma_f32_16x16x32_bf16 v[156:159], v[176:179], v[74:77], v[156:159]
	s_nop 0
	v_readlane_b32 s96, v254, 60
	v_readlane_b32 s97, v254, 61
	s_nop 0
	s_waitcnt lgkmcnt(4)
	v_mfma_f32_16x16x32_bf16 v[156:159], v[238:241], v[70:73], v[156:159]
	s_nop 0
	ds_read_b128 v[238:241], v149 offset:192
	v_lshl_add_u64 v[110:111], s[96:97], 0, v[110:111]
	v_readlane_b32 s96, v254, 19
	s_nop 0
	s_waitcnt lgkmcnt(4)
	v_mfma_f32_16x16x32_bf16 v[156:159], v[242:245], v[66:69], v[156:159]
	s_nop 0
	ds_read_b128 v[242:245], v148 offset:4416
	v_div_fixup_f32 v100, v100, v99, 1.0
	v_cndmask_b32_e64 v111, v111, v113, s[6:7]
	s_nop 4
	v_pk_mul_f32 v[158:159], v[98:99], v[158:159] op_sel_hi:[0,1]
	v_pk_mul_f32 v[156:157], v[98:99], v[156:157] op_sel_hi:[0,1]
	v_cndmask_b32_e64 v110, v110, v112, s[6:7]
	v_readlane_b32 s97, v254, 20
	s_nop 0
	s_waitcnt lgkmcnt(4)
	v_mfma_f32_16x16x32_bf16 v[156:159], v[246:249], v[82:85], v[156:159]
	s_nop 0
	ds_read_b128 v[246:249], v148 offset:4352
	v_lshl_add_u64 v[110:111], v[110:111], 0, s[96:97]
	v_lshl_add_u64 v[110:111], v[110:111], 0, v[0:1]
	s_nop 0
	s_waitcnt lgkmcnt(4)
	v_mfma_f32_16x16x32_bf16 v[156:159], v[250:253], v[86:89], v[156:159]
	s_nop 0
	ds_read_b128 v[250:253], v148 offset:4480
	s_nop 0
	s_waitcnt lgkmcnt(4)
	v_mfma_f32_16x16x32_bf16 v[156:159], v[234:237], v[90:93], v[156:159]
	s_nop 0
	ds_read_b128 v[234:237], v148 offset:4544
	s_nop 0
	s_waitcnt lgkmcnt(4)
	v_mfma_f32_16x16x32_bf16 v[156:159], v[238:241], v[94:97], v[156:159]
	s_nop 0
	ds_read_b128 v[238:241], v149 offset:4352
	s_nop 6
	v_pk_mul_f32 v[112:113], v[100:101], v[158:159] op_sel_hi:[0,1]
	v_pk_mul_f32 v[156:157], v[100:101], v[156:157] op_sel_hi:[0,1]
	v_cvt_pk_bf16_f32 v156, v156, v157
	v_cvt_pk_bf16_f32 v157, v112, v113
	global_store_dwordx2 v[110:111], v[156:157], off
	s_nop 0
	s_nop 0
	s_waitcnt lgkmcnt(3)
	v_mfma_f32_16x16x32_bf16 v[156:159], v[246:249], v[78:81], 0
	ds_read_b128 v[246:249], v149 offset:4416
	v_mfma_f32_16x16x32_bf16 v[156:159], v[242:245], v[74:77], v[156:159]
	s_nop 0
	ds_read_b128 v[242:245], v149 offset:4480
	s_nop 0
	s_waitcnt lgkmcnt(4)
	v_mfma_f32_16x16x32_bf16 v[156:159], v[250:253], v[70:73], v[156:159]
	s_nop 0
	ds_read_b128 v[250:253], v149 offset:4544
	s_nop 0
	s_waitcnt lgkmcnt(4)
	v_mfma_f32_16x16x32_bf16 v[156:159], v[234:237], v[66:69], v[156:159]
	s_nop 0
	ds_read_b128 v[234:237], v148 offset:8768
	s_nop 6
	v_pk_mul_f32 v[158:159], v[98:99], v[158:159] op_sel_hi:[0,1]
	v_pk_mul_f32 v[156:157], v[98:99], v[156:157] op_sel_hi:[0,1]
	s_nop 0
	s_nop 0
	s_waitcnt lgkmcnt(4)
	v_mfma_f32_16x16x32_bf16 v[156:159], v[238:241], v[82:85], v[156:159]
	s_nop 0
	ds_read_b128 v[238:241], v148 offset:8704
	s_nop 0
	s_waitcnt lgkmcnt(4)
	v_mfma_f32_16x16x32_bf16 v[156:159], v[246:249], v[86:89], v[156:159]
	s_nop 0
	ds_read_b128 v[246:249], v148 offset:8832
	s_nop 0
	s_waitcnt lgkmcnt(4)
	v_mfma_f32_16x16x32_bf16 v[156:159], v[242:245], v[90:93], v[156:159]
	s_nop 0
	ds_read_b128 v[242:245], v148 offset:8896
	s_nop 0
	s_waitcnt lgkmcnt(4)
	v_mfma_f32_16x16x32_bf16 v[156:159], v[250:253], v[94:97], v[156:159]
	s_nop 0
	ds_read_b128 v[250:253], v149 offset:8704
	s_nop 6
	v_pk_mul_f32 v[112:113], v[100:101], v[158:159] op_sel_hi:[0,1]
	v_pk_mul_f32 v[156:157], v[100:101], v[156:157] op_sel_hi:[0,1]
	v_cvt_pk_bf16_f32 v156, v156, v157
	v_cvt_pk_bf16_f32 v157, v112, v113
	global_store_dwordx2 v[110:111], v[156:157], off offset:32
	s_nop 0
	s_nop 0
	s_waitcnt lgkmcnt(3)
	v_mfma_f32_16x16x32_bf16 v[156:159], v[238:241], v[78:81], 0
	ds_read_b128 v[238:241], v149 offset:8768
	v_mfma_f32_16x16x32_bf16 v[156:159], v[234:237], v[74:77], v[156:159]
	s_nop 0
	ds_read_b128 v[234:237], v149 offset:8832
	s_nop 0
	s_waitcnt lgkmcnt(4)
	v_mfma_f32_16x16x32_bf16 v[156:159], v[246:249], v[70:73], v[156:159]
	s_nop 0
	ds_read_b128 v[246:249], v149 offset:8896
	s_nop 0
	s_waitcnt lgkmcnt(4)
	v_mfma_f32_16x16x32_bf16 v[156:159], v[242:245], v[66:69], v[156:159]
	s_nop 0
	ds_read_b128 v[242:245], v148 offset:13120
	s_nop 6
	v_pk_mul_f32 v[158:159], v[98:99], v[158:159] op_sel_hi:[0,1]
	v_pk_mul_f32 v[156:157], v[98:99], v[156:157] op_sel_hi:[0,1]
	s_nop 0
	s_nop 0
	s_waitcnt lgkmcnt(4)
	v_mfma_f32_16x16x32_bf16 v[156:159], v[250:253], v[82:85], v[156:159]
	s_nop 0
	ds_read_b128 v[250:253], v148 offset:13056
	s_nop 0
	s_waitcnt lgkmcnt(4)
	v_mfma_f32_16x16x32_bf16 v[156:159], v[238:241], v[86:89], v[156:159]
	s_nop 0
	ds_read_b128 v[238:241], v148 offset:13184
	s_nop 0
	s_waitcnt lgkmcnt(4)
	v_mfma_f32_16x16x32_bf16 v[156:159], v[234:237], v[90:93], v[156:159]
	s_nop 0
	ds_read_b128 v[234:237], v148 offset:13248
	s_nop 0
	s_waitcnt lgkmcnt(4)
	v_mfma_f32_16x16x32_bf16 v[156:159], v[246:249], v[94:97], v[156:159]
	s_nop 0
	ds_read_b128 v[246:249], v149 offset:13056
	s_nop 6
	v_pk_mul_f32 v[112:113], v[100:101], v[158:159] op_sel_hi:[0,1]
	v_pk_mul_f32 v[156:157], v[100:101], v[156:157] op_sel_hi:[0,1]
	v_cvt_pk_bf16_f32 v156, v156, v157
	v_cvt_pk_bf16_f32 v157, v112, v113
	global_store_dwordx2 v[110:111], v[156:157], off offset:64
	s_nop 0
	s_nop 0
	s_waitcnt lgkmcnt(3)
	v_mfma_f32_16x16x32_bf16 v[156:159], v[250:253], v[78:81], 0
	ds_read_b128 v[250:253], v149 offset:13120
	v_mfma_f32_16x16x32_bf16 v[156:159], v[242:245], v[74:77], v[156:159]
	s_nop 0
	ds_read_b128 v[242:245], v149 offset:13184
	s_nop 0
	s_waitcnt lgkmcnt(4)
	v_mfma_f32_16x16x32_bf16 v[156:159], v[238:241], v[70:73], v[156:159]
	s_nop 0
	ds_read_b128 v[238:241], v149 offset:13248
	s_nop 0
	s_waitcnt lgkmcnt(4)
	v_mfma_f32_16x16x32_bf16 v[156:159], v[234:237], v[66:69], v[156:159]
	s_nop 0
	ds_read_b128 v[234:237], v148 offset:17472
	s_nop 6
	v_pk_mul_f32 v[158:159], v[98:99], v[158:159] op_sel_hi:[0,1]
	v_pk_mul_f32 v[156:157], v[98:99], v[156:157] op_sel_hi:[0,1]
	s_nop 0
	s_nop 0
	s_waitcnt lgkmcnt(4)
	v_mfma_f32_16x16x32_bf16 v[156:159], v[246:249], v[82:85], v[156:159]
	s_nop 0
	ds_read_b128 v[246:249], v148 offset:17408
	s_nop 0
	s_waitcnt lgkmcnt(4)
	v_mfma_f32_16x16x32_bf16 v[156:159], v[250:253], v[86:89], v[156:159]
	s_nop 0
	ds_read_b128 v[250:253], v148 offset:17536
	s_nop 0
	s_waitcnt lgkmcnt(4)
	v_mfma_f32_16x16x32_bf16 v[156:159], v[242:245], v[90:93], v[156:159]
	s_nop 0
	ds_read_b128 v[242:245], v148 offset:17600
	s_nop 0
	s_waitcnt lgkmcnt(4)
	v_mfma_f32_16x16x32_bf16 v[156:159], v[238:241], v[94:97], v[156:159]
	s_nop 0
	ds_read_b128 v[238:241], v149 offset:17408
	s_nop 6
	v_pk_mul_f32 v[112:113], v[100:101], v[158:159] op_sel_hi:[0,1]
	v_pk_mul_f32 v[156:157], v[100:101], v[156:157] op_sel_hi:[0,1]
	v_cvt_pk_bf16_f32 v156, v156, v157
	v_cvt_pk_bf16_f32 v157, v112, v113
	global_store_dwordx2 v[110:111], v[156:157], off offset:96
	s_nop 0
	s_nop 0
	s_waitcnt lgkmcnt(3)
	v_mfma_f32_16x16x32_bf16 v[156:159], v[246:249], v[78:81], 0
	ds_read_b128 v[246:249], v149 offset:17472
	v_mfma_f32_16x16x32_bf16 v[156:159], v[234:237], v[74:77], v[156:159]
	s_nop 0
	ds_read_b128 v[234:237], v149 offset:17536
	s_nop 0
	s_waitcnt lgkmcnt(4)
	v_mfma_f32_16x16x32_bf16 v[156:159], v[250:253], v[70:73], v[156:159]
	s_nop 0
	ds_read_b128 v[250:253], v149 offset:17600
	s_nop 0
	s_waitcnt lgkmcnt(4)
	v_mfma_f32_16x16x32_bf16 v[156:159], v[242:245], v[66:69], v[156:159]
	s_nop 0
	ds_read_b128 v[242:245], v148 offset:21824
	s_nop 6
	v_pk_mul_f32 v[158:159], v[98:99], v[158:159] op_sel_hi:[0,1]
	v_pk_mul_f32 v[156:157], v[98:99], v[156:157] op_sel_hi:[0,1]
	s_nop 0
	s_nop 0
	s_waitcnt lgkmcnt(4)
	v_mfma_f32_16x16x32_bf16 v[156:159], v[238:241], v[82:85], v[156:159]
	s_nop 0
	ds_read_b128 v[238:241], v148 offset:21760
	s_nop 0
	s_waitcnt lgkmcnt(4)
	v_mfma_f32_16x16x32_bf16 v[156:159], v[246:249], v[86:89], v[156:159]
	s_nop 0
	ds_read_b128 v[246:249], v148 offset:21888
	s_nop 0
	s_waitcnt lgkmcnt(4)
	v_mfma_f32_16x16x32_bf16 v[156:159], v[234:237], v[90:93], v[156:159]
	s_nop 0
	ds_read_b128 v[234:237], v148 offset:21952
	s_nop 0
	s_waitcnt lgkmcnt(4)
	v_mfma_f32_16x16x32_bf16 v[156:159], v[250:253], v[94:97], v[156:159]
	s_nop 0
	ds_read_b128 v[250:253], v149 offset:21760
	s_nop 6
	v_pk_mul_f32 v[112:113], v[100:101], v[158:159] op_sel_hi:[0,1]
	v_pk_mul_f32 v[156:157], v[100:101], v[156:157] op_sel_hi:[0,1]
	v_cvt_pk_bf16_f32 v156, v156, v157
	v_cvt_pk_bf16_f32 v157, v112, v113
	global_store_dwordx2 v[110:111], v[156:157], off offset:128
	s_nop 0
	s_nop 0
	s_waitcnt lgkmcnt(3)
	v_mfma_f32_16x16x32_bf16 v[156:159], v[238:241], v[78:81], 0
	ds_read_b128 v[238:241], v149 offset:21824
	v_mfma_f32_16x16x32_bf16 v[156:159], v[242:245], v[74:77], v[156:159]
	s_nop 0
	ds_read_b128 v[242:245], v149 offset:21888
	s_nop 0
	s_waitcnt lgkmcnt(4)
	v_mfma_f32_16x16x32_bf16 v[156:159], v[246:249], v[70:73], v[156:159]
	s_nop 0
	ds_read_b128 v[246:249], v149 offset:21952
	s_nop 0
	s_waitcnt lgkmcnt(4)
	v_mfma_f32_16x16x32_bf16 v[156:159], v[234:237], v[66:69], v[156:159]
	s_nop 0
	ds_read_b128 v[234:237], v148 offset:26176
	s_nop 6
	v_pk_mul_f32 v[158:159], v[98:99], v[158:159] op_sel_hi:[0,1]
	v_pk_mul_f32 v[156:157], v[98:99], v[156:157] op_sel_hi:[0,1]
	s_nop 0
	s_nop 0
	s_waitcnt lgkmcnt(4)
	v_mfma_f32_16x16x32_bf16 v[156:159], v[250:253], v[82:85], v[156:159]
	s_nop 0
	ds_read_b128 v[250:253], v148 offset:26112
	s_nop 0
	s_waitcnt lgkmcnt(4)
	v_mfma_f32_16x16x32_bf16 v[156:159], v[238:241], v[86:89], v[156:159]
	s_nop 0
	ds_read_b128 v[238:241], v148 offset:26240
	s_nop 0
	s_waitcnt lgkmcnt(4)
	v_mfma_f32_16x16x32_bf16 v[156:159], v[242:245], v[90:93], v[156:159]
	s_nop 0
	ds_read_b128 v[242:245], v148 offset:26304
	s_nop 0
	s_waitcnt lgkmcnt(4)
	v_mfma_f32_16x16x32_bf16 v[156:159], v[246:249], v[94:97], v[156:159]
	s_nop 0
	ds_read_b128 v[246:249], v149 offset:26112
	s_nop 6
	v_pk_mul_f32 v[112:113], v[100:101], v[158:159] op_sel_hi:[0,1]
	v_pk_mul_f32 v[156:157], v[100:101], v[156:157] op_sel_hi:[0,1]
	v_cvt_pk_bf16_f32 v156, v156, v157
	v_cvt_pk_bf16_f32 v157, v112, v113
	global_store_dwordx2 v[110:111], v[156:157], off offset:160
	s_nop 0
	s_nop 0
	s_waitcnt lgkmcnt(3)
	v_mfma_f32_16x16x32_bf16 v[156:159], v[250:253], v[78:81], 0
	ds_read_b128 v[250:253], v149 offset:26176
	v_mfma_f32_16x16x32_bf16 v[156:159], v[234:237], v[74:77], v[156:159]
	s_nop 0
	ds_read_b128 v[234:237], v149 offset:26240
	s_nop 0
	s_waitcnt lgkmcnt(4)
	v_mfma_f32_16x16x32_bf16 v[156:159], v[238:241], v[70:73], v[156:159]
	s_nop 0
	ds_read_b128 v[238:241], v148 offset:30464
	s_nop 0
	s_waitcnt lgkmcnt(4)
	v_mfma_f32_16x16x32_bf16 v[156:159], v[242:245], v[66:69], v[156:159]
	s_nop 0
	s_nop 6
	v_pk_mul_f32 v[158:159], v[98:99], v[158:159] op_sel_hi:[0,1]
	v_pk_mul_f32 v[156:157], v[98:99], v[156:157] op_sel_hi:[0,1]
	s_nop 0
	s_nop 0
	s_waitcnt lgkmcnt(3)
	v_mfma_f32_16x16x32_bf16 v[156:159], v[246:249], v[82:85], v[156:159]
	s_nop 0
	ds_read_b128 v[242:245], v148 offset:30592
	s_nop 0
	s_waitcnt lgkmcnt(3)
	v_mfma_f32_16x16x32_bf16 v[156:159], v[250:253], v[86:89], v[156:159]
	s_nop 0
	ds_read_b128 v[246:249], v148 offset:30656
	s_nop 0
	s_waitcnt lgkmcnt(3)
	v_mfma_f32_16x16x32_bf16 v[156:159], v[234:237], v[90:93], v[156:159]
	ds_read_b128 v[234:237], v149 offset:30464
	ds_read_b128 v[176:179], v149 offset:26304
	s_nop 0
	s_waitcnt lgkmcnt(0)
	v_mfma_f32_16x16x32_bf16 v[156:159], v[176:179], v[94:97], v[156:159]
	s_nop 7
	v_pk_mul_f32 v[112:113], v[100:101], v[158:159] op_sel_hi:[0,1]
	v_pk_mul_f32 v[156:157], v[100:101], v[156:157] op_sel_hi:[0,1]
	v_cvt_pk_bf16_f32 v156, v156, v157
	v_cvt_pk_bf16_f32 v157, v112, v113
	global_store_dwordx2 v[110:111], v[156:157], off offset:192
	s_nop 0
	ds_read_b128 v[250:253], v149 offset:30528
	s_nop 0
	v_mfma_f32_16x16x32_bf16 v[78:81], v[238:241], v[78:81], 0
	ds_read_b128 v[238:241], v149 offset:30592
	ds_read_b128 v[156:159], v148 offset:30528
	s_nop 0
	s_waitcnt lgkmcnt(0)
	v_mfma_f32_16x16x32_bf16 v[74:77], v[156:159], v[74:77], v[78:81]
	s_nop 4
	s_nop 0
	s_nop 0
	v_mfma_f32_16x16x32_bf16 v[70:73], v[242:245], v[70:73], v[74:77]
	ds_read_b128 v[242:245], v149 offset:30656
	s_nop 2
	s_nop 0
	s_nop 0
	v_mfma_f32_16x16x32_bf16 v[66:69], v[246:249], v[66:69], v[70:73]
	s_nop 2
	s_nop 0
	s_nop 3
	v_pk_mul_f32 v[68:69], v[98:99], v[68:69] op_sel_hi:[0,1]
	v_pk_mul_f32 v[66:67], v[98:99], v[66:67] op_sel_hi:[0,1]
	s_nop 0
	s_nop 0
	v_mfma_f32_16x16x32_bf16 v[66:69], v[234:237], v[82:85], v[66:69]
	s_nop 0
	s_nop 0
	v_mfma_f32_16x16x32_bf16 v[66:69], v[250:253], v[86:89], v[66:69]
	s_nop 0
	s_nop 0
	v_mfma_f32_16x16x32_bf16 v[66:69], v[238:241], v[90:93], v[66:69]
	s_nop 0
	ds_read_b128 v[234:237], v151 offset:34816
	s_nop 0
	s_waitcnt lgkmcnt(1)
	v_mfma_f32_16x16x32_bf16 v[66:69], v[242:245], v[94:97], v[66:69]
	s_nop 7
	v_pk_mul_f32 v[68:69], v[100:101], v[68:69] op_sel_hi:[0,1]
	v_pk_mul_f32 v[66:67], v[100:101], v[66:67] op_sel_hi:[0,1]
	v_cvt_pk_bf16_f32 v66, v66, v67
	v_cvt_pk_bf16_f32 v67, v68, v69
	global_store_dwordx2 v[110:111], v[66:67], off offset:224
	v_sub_f32_e32 v66, v154, v152
	v_mul_f32_e32 v82, 0x3fb8aa3b, v66
	ds_read_b128 v[238:241], v151 offset:34880
	ds_read_b128 v[78:81], v150
	ds_read_b128 v[242:245], v151 offset:34944
	ds_read_b128 v[74:77], v150 offset:64
	ds_read_b128 v[246:249], v151 offset:35008
	ds_read_b128 v[70:73], v150 offset:128
	ds_read_b128 v[250:253], v151 offset:39168
	ds_read_b128 v[66:69], v150 offset:192
	v_exp_f32_e32 v82, v82
	s_nop 0
	v_pk_mul_f32 v[4:5], v[4:5], v[82:83] op_sel_hi:[1,0]
	v_pk_mul_f32 v[2:3], v[2:3], v[82:83] op_sel_hi:[1,0]
	v_pk_mul_f32 v[8:9], v[8:9], v[82:83] op_sel_hi:[1,0]
	v_pk_mul_f32 v[6:7], v[6:7], v[82:83] op_sel_hi:[1,0]
	s_nop 0
	s_waitcnt lgkmcnt(6)
	v_mfma_f32_16x16x32_bf16 v[2:5], v[78:81], v[234:237], v[2:5]
	s_nop 0
	ds_read_b128 v[234:237], v151 offset:39232
	v_pk_mul_f32 v[12:13], v[12:13], v[82:83] op_sel_hi:[1,0]
	v_pk_mul_f32 v[10:11], v[10:11], v[82:83] op_sel_hi:[1,0]
	s_nop 0
	s_waitcnt lgkmcnt(5)
	v_mfma_f32_16x16x32_bf16 v[2:5], v[74:77], v[238:241], v[2:5]
	s_nop 0
	ds_read_b128 v[238:241], v151 offset:39296
	v_pk_mul_f32 v[16:17], v[16:17], v[82:83] op_sel_hi:[1,0]
	v_pk_mul_f32 v[14:15], v[14:15], v[82:83] op_sel_hi:[1,0]
	s_nop 0
	s_waitcnt lgkmcnt(4)
	v_mfma_f32_16x16x32_bf16 v[2:5], v[70:73], v[242:245], v[2:5]
	s_nop 0
	ds_read_b128 v[242:245], v151 offset:39360
	v_pk_mul_f32 v[20:21], v[20:21], v[82:83] op_sel_hi:[1,0]
	v_pk_mul_f32 v[18:19], v[18:19], v[82:83] op_sel_hi:[1,0]
	s_nop 0
	s_waitcnt lgkmcnt(3)
	v_mfma_f32_16x16x32_bf16 v[2:5], v[66:69], v[246:249], v[2:5]
	s_nop 0
	ds_read_b128 v[246:249], v151 offset:43520
	v_pk_mul_f32 v[24:25], v[24:25], v[82:83] op_sel_hi:[1,0]
	v_pk_mul_f32 v[22:23], v[22:23], v[82:83] op_sel_hi:[1,0]
	s_nop 0
	v_mfma_f32_16x16x32_bf16 v[6:9], v[78:81], v[250:253], v[6:9]
	s_nop 0
	ds_read_b128 v[250:253], v151 offset:43584
	v_pk_mul_f32 v[28:29], v[28:29], v[82:83] op_sel_hi:[1,0]
	v_pk_mul_f32 v[26:27], v[26:27], v[82:83] op_sel_hi:[1,0]
	s_nop 0
	s_waitcnt lgkmcnt(4)
	v_mfma_f32_16x16x32_bf16 v[6:9], v[74:77], v[234:237], v[6:9]
	s_nop 0
	ds_read_b128 v[234:237], v151 offset:43648
	v_pk_mul_f32 v[32:33], v[32:33], v[82:83] op_sel_hi:[1,0]
	v_pk_mul_f32 v[30:31], v[30:31], v[82:83] op_sel_hi:[1,0]
	s_nop 0
	s_waitcnt lgkmcnt(4)
	v_mfma_f32_16x16x32_bf16 v[6:9], v[70:73], v[238:241], v[6:9]
	s_nop 0
	ds_read_b128 v[238:241], v151 offset:43712
	s_nop 0
	s_waitcnt lgkmcnt(4)
	v_mfma_f32_16x16x32_bf16 v[6:9], v[66:69], v[242:245], v[6:9]
	s_nop 0
	ds_read_b128 v[242:245], v151 offset:47872
	s_nop 0
	s_waitcnt lgkmcnt(4)
	v_mfma_f32_16x16x32_bf16 v[10:13], v[78:81], v[246:249], v[10:13]
	s_nop 0
	ds_read_b128 v[246:249], v151 offset:47936
	s_nop 0
	s_waitcnt lgkmcnt(4)
	v_mfma_f32_16x16x32_bf16 v[10:13], v[74:77], v[250:253], v[10:13]
	s_nop 0
	ds_read_b128 v[250:253], v151 offset:48000
	s_nop 0
	s_waitcnt lgkmcnt(4)
	v_mfma_f32_16x16x32_bf16 v[10:13], v[70:73], v[234:237], v[10:13]
	s_nop 0
	ds_read_b128 v[234:237], v151 offset:48064
	s_nop 0
	s_waitcnt lgkmcnt(4)
	v_mfma_f32_16x16x32_bf16 v[10:13], v[66:69], v[238:241], v[10:13]
	s_nop 0
	ds_read_b128 v[238:241], v151 offset:52224
	s_nop 0
	s_waitcnt lgkmcnt(4)
	v_mfma_f32_16x16x32_bf16 v[14:17], v[78:81], v[242:245], v[14:17]
	s_nop 0
	ds_read_b128 v[242:245], v151 offset:52288
	s_nop 0
	s_waitcnt lgkmcnt(4)
	v_mfma_f32_16x16x32_bf16 v[14:17], v[74:77], v[246:249], v[14:17]
	s_nop 0
	ds_read_b128 v[246:249], v151 offset:52352
	s_nop 0
	s_waitcnt lgkmcnt(4)
	v_mfma_f32_16x16x32_bf16 v[14:17], v[70:73], v[250:253], v[14:17]
	s_nop 0
	ds_read_b128 v[250:253], v151 offset:52416
	s_nop 0
	s_waitcnt lgkmcnt(4)
	v_mfma_f32_16x16x32_bf16 v[14:17], v[66:69], v[234:237], v[14:17]
	s_nop 0
	ds_read_b128 v[234:237], v151 offset:56576
	s_nop 0
	s_waitcnt lgkmcnt(4)
	v_mfma_f32_16x16x32_bf16 v[18:21], v[78:81], v[238:241], v[18:21]
	s_nop 0
	ds_read_b128 v[238:241], v151 offset:56640
	s_nop 0
	s_waitcnt lgkmcnt(4)
	v_mfma_f32_16x16x32_bf16 v[18:21], v[74:77], v[242:245], v[18:21]
	s_nop 0
	ds_read_b128 v[242:245], v151 offset:56704
	s_nop 0
	s_waitcnt lgkmcnt(4)
	v_mfma_f32_16x16x32_bf16 v[18:21], v[70:73], v[246:249], v[18:21]
	s_nop 0
	ds_read_b128 v[246:249], v151 offset:56768
	s_nop 0
	s_waitcnt lgkmcnt(4)
	v_mfma_f32_16x16x32_bf16 v[18:21], v[66:69], v[250:253], v[18:21]
	s_nop 0
	ds_read_b128 v[250:253], v151 offset:60928
	s_nop 0
	s_waitcnt lgkmcnt(4)
	v_mfma_f32_16x16x32_bf16 v[22:25], v[78:81], v[234:237], v[22:25]
	s_nop 0
	ds_read_b128 v[234:237], v151 offset:60992
	s_nop 0
	s_waitcnt lgkmcnt(4)
	v_mfma_f32_16x16x32_bf16 v[22:25], v[74:77], v[238:241], v[22:25]
	s_nop 0
	ds_read_b128 v[238:241], v151 offset:61056
	s_nop 0
	s_waitcnt lgkmcnt(4)
	v_mfma_f32_16x16x32_bf16 v[22:25], v[70:73], v[242:245], v[22:25]
	s_nop 0
	ds_read_b128 v[242:245], v151 offset:61120
	s_nop 0
	s_waitcnt lgkmcnt(4)
	v_mfma_f32_16x16x32_bf16 v[22:25], v[66:69], v[246:249], v[22:25]
	s_nop 0
	s_nop 0
	s_waitcnt lgkmcnt(3)
	v_mfma_f32_16x16x32_bf16 v[26:29], v[78:81], v[250:253], v[26:29]
	s_nop 0
	s_nop 0
	s_waitcnt lgkmcnt(2)
	v_mfma_f32_16x16x32_bf16 v[26:29], v[74:77], v[234:237], v[26:29]
	s_nop 0
	s_nop 0
	s_waitcnt lgkmcnt(1)
	v_mfma_f32_16x16x32_bf16 v[26:29], v[70:73], v[238:241], v[26:29]
	s_nop 0
	s_nop 0
	s_waitcnt lgkmcnt(0)
	v_mfma_f32_16x16x32_bf16 v[26:29], v[66:69], v[242:245], v[26:29]
	ds_read_b128 v[84:87], v151 offset:65280
	s_nop 0
	s_waitcnt lgkmcnt(0)
	v_mfma_f32_16x16x32_bf16 v[30:33], v[78:81], v[84:87], v[30:33]
	ds_read_b128 v[78:81], v151 offset:65344
	s_nop 0
	s_waitcnt lgkmcnt(0)
	v_mfma_f32_16x16x32_bf16 v[30:33], v[74:77], v[78:81], v[30:33]
	ds_read_b128 v[74:77], v151 offset:65408
	s_nop 0
	s_waitcnt lgkmcnt(0)
	v_mfma_f32_16x16x32_bf16 v[30:33], v[70:73], v[74:77], v[30:33]
	ds_read_b128 v[70:73], v151 offset:65472
	s_nop 0
	s_waitcnt lgkmcnt(0)
	v_mfma_f32_16x16x32_bf16 v[30:33], v[66:69], v[70:73], v[30:33]
	v_lshrrev_b32_e32 v66, 6, v163
	v_and_b32_e32 v67, 15, v163
	v_lshl_add_u32 v66, v66, 4, v67
	v_bfe_u32 v67, v163, 4, 2
	v_mul_u32_u24_e32 v68, 0x110, v66
	v_lshl_add_u32 v67, v67, 4, v68
	v_lshlrev_b32_e32 v66, 2, v66
	v_add_u32_e32 v66, 0x22600, v66
	v_mov_b32_e32 v76, 0x3f803f80
	v_mov_b32_e32 v77, 0x3f803f80
	v_mov_b32_e32 v78, 0x3f803f80
	v_mov_b32_e32 v79, 0x3f803f80
	ds_read_b128 v[68:71], v67 offset:34816
	ds_read_b128 v[72:75], v67 offset:34880
	s_waitcnt lgkmcnt(1)
	v_mfma_f32_16x16x32_bf16 v[84:87], v[76:79], v[68:71], 0
	ds_read_b128 v[68:71], v67 offset:34944
	s_waitcnt lgkmcnt(1)
	v_mfma_f32_16x16x32_bf16 v[84:87], v[76:79], v[72:75], v[84:87]
	ds_read_b128 v[72:75], v67 offset:35008
	ds_read_b32 v67, v66
	s_waitcnt lgkmcnt(2)
	v_mfma_f32_16x16x32_bf16 v[84:87], v[76:79], v[68:71], v[84:87]
	s_waitcnt lgkmcnt(1)
	v_mfma_f32_16x16x32_bf16 v[84:87], v[76:79], v[72:75], v[84:87]
	s_waitcnt lgkmcnt(0)
	s_nop 7
	s_nop 1
	v_fmac_f32_e32 v84, v82, v67
